# counted lgkmcnt/vmcnt waits in MLA attention stage body; adaLN prologue: batched silu(c) gather and depth-4 register prefetch of w_ada rows (all bit-identical)
# speedup vs baseline: 1.0098x; 1.0098x over previous
.LBB0_178:
	v_exp_f32_e32 v68, v80
	v_exp_f32_e32 v69, v81
	v_exp_f32_e32 v72, v82
	v_exp_f32_e32 v73, v83
	v_add_f32_e32 v70, 0, v68
	v_add_f32_e32 v71, 0, v69
	v_cvt_pk_bf16_f32 v176, v68, v69
	ds_read_b128 v[180:183], v220 offset:19968
	ds_read_b128 v[64:67], v220 offset:13312
	ds_read_b128 v[184:187], v220 offset:13344
	v_cvt_pk_bf16_f32 v177, v72, v73
	v_add_f32_e32 v68, v72, v70
	v_add_f32_e32 v69, v73, v71
	v_exp_f32_e32 v70, v84
	v_exp_f32_e32 v71, v85
	s_nop 0
	v_add_f32_e32 v68, v70, v68
	v_add_f32_e32 v69, v71, v69
	v_cvt_pk_bf16_f32 v178, v70, v71
	s_waitcnt lgkmcnt(1)
	v_mfma_f32_32x32x16_bf16 v[96:111], v[64:67], v[120:123], v[32:47]
	v_exp_f32_e32 v70, v86
	v_exp_f32_e32 v71, v87
	ds_read_b128 v[80:83], v220 offset:20000
	v_add_f32_e32 v188, v70, v68
	v_add_f32_e32 v189, v71, v69
	v_cvt_pk_bf16_f32 v179, v70, v71
	v_mfma_f32_32x32x16_bf16 v[64:79], v[180:183], v[120:123], v[32:47]
	v_exp_f32_e32 v89, v89
	v_exp_f32_e32 v88, v88
	ds_read_b128 v[84:87], v220 offset:13376
	v_add_f32_e32 v182, v89, v189
	v_add_f32_e32 v181, v88, v188
	v_cvt_pk_bf16_f32 v180, v88, v89
	s_waitcnt lgkmcnt(2)
	v_mfma_f32_32x32x16_bf16 v[96:111], v[184:187], v[124:127], v[96:111]
	ds_read_b128 v[188:191], v220 offset:20032
	v_exp_f32_e32 v88, v91
	v_exp_f32_e32 v89, v90
	v_add_f32_e32 v182, v88, v182
	v_add_f32_e32 v183, v89, v181
	v_cvt_pk_bf16_f32 v181, v89, v88
	s_waitcnt lgkmcnt(2)
	v_mfma_f32_32x32x16_bf16 v[64:79], v[80:83], v[124:127], v[64:79]
	v_exp_f32_e32 v80, v93
	v_exp_f32_e32 v81, v92
	ds_read_b128 v[88:91], v220 offset:13408
	v_add_f32_e32 v93, v80, v182
	v_add_f32_e32 v92, v81, v183
	v_cvt_pk_bf16_f32 v182, v81, v80
	s_waitcnt lgkmcnt(2)
	v_mfma_f32_32x32x16_bf16 v[96:111], v[84:87], v[128:131], v[96:111]
	v_exp_f32_e32 v94, v94
	v_exp_f32_e32 v95, v95
	ds_read_b128 v[80:83], v220 offset:20064
	v_add_f32_e32 v92, v94, v92
	v_add_f32_e32 v93, v95, v93
	v_cvt_pk_bf16_f32 v183, v94, v95
	s_waitcnt lgkmcnt(2)
	v_mfma_f32_32x32x16_bf16 v[64:79], v[188:191], v[128:131], v[64:79]
	v_exp_f32_e32 v49, v49
	v_exp_f32_e32 v48, v48
	ds_read_b128 v[84:87], v220 offset:13440
	v_add_f32_e32 v186, v49, v93
	v_add_f32_e32 v185, v48, v92
	v_cvt_pk_bf16_f32 v184, v48, v49
	s_waitcnt lgkmcnt(2)
	v_mfma_f32_32x32x16_bf16 v[96:111], v[88:91], v[132:135], v[96:111]
	v_exp_f32_e32 v48, v51
	v_exp_f32_e32 v49, v50
	ds_read_b128 v[92:95], v220 offset:20096
	v_add_f32_e32 v89, v48, v186
	v_add_f32_e32 v88, v49, v185
	v_cvt_pk_bf16_f32 v185, v49, v48
	s_waitcnt lgkmcnt(2)
	v_mfma_f32_32x32x16_bf16 v[64:79], v[80:83], v[132:135], v[64:79]
	ds_read_b128 v[48:51], v220 offset:13472
	v_exp_f32_e32 v53, v53
	v_exp_f32_e32 v52, v52
	v_add_f32_e32 v89, v53, v89
	v_add_f32_e32 v88, v52, v88
	v_cvt_pk_bf16_f32 v186, v52, v53
	s_waitcnt lgkmcnt(2)
	v_mfma_f32_32x32x16_bf16 v[96:111], v[84:87], v[136:139], v[96:111]
	v_exp_f32_e32 v52, v55
	v_exp_f32_e32 v53, v54
	ds_read_b128 v[80:83], v220 offset:20128
	v_add_f32_e32 v55, v52, v89
	v_add_f32_e32 v54, v53, v88
	v_cvt_pk_bf16_f32 v187, v53, v52
	s_waitcnt lgkmcnt(2)
	v_mfma_f32_32x32x16_bf16 v[64:79], v[92:95], v[136:139], v[64:79]
	v_exp_f32_e32 v52, v57
	v_exp_f32_e32 v53, v56
	ds_read_b128 v[84:87], v221 offset:35840
	v_add_f32_e32 v55, v52, v55
	v_add_f32_e32 v54, v53, v54
	v_cvt_pk_bf16_f32 v188, v53, v52
	s_waitcnt lgkmcnt(2)
	v_mfma_f32_32x32x16_bf16 v[96:111], v[48:51], v[140:143], v[96:111]
	v_exp_f32_e32 v48, v59
	v_exp_f32_e32 v49, v58
	ds_read_b128 v[88:91], v221 offset:40448
	v_add_f32_e32 v51, v48, v55
	v_add_f32_e32 v50, v49, v54
	v_cvt_pk_bf16_f32 v189, v49, v48
	s_waitcnt lgkmcnt(2)
	v_mfma_f32_32x32x16_bf16 v[64:79], v[80:83], v[140:143], v[64:79]
	ds_read_b128 v[52:55], v221 offset:35872
	v_exp_f32_e32 v48, v61
	v_exp_f32_e32 v49, v60
	v_add_f32_e32 v51, v48, v51
	v_add_f32_e32 v50, v49, v50
	v_cvt_pk_bf16_f32 v190, v49, v48
	s_waitcnt lgkmcnt(2)
	v_mfma_f32_32x32x16_bf16 v[0:15], v[84:87], v[164:167], v[0:15]
	v_exp_f32_e32 v48, v62
	v_exp_f32_e32 v49, v63
	ds_read_b128 v[60:63], v221 offset:40480
	v_add_f32_e32 v223, v48, v50
	v_add_f32_e32 v233, v49, v51
	v_cvt_pk_bf16_f32 v191, v48, v49
	s_waitcnt lgkmcnt(2)
	v_mfma_f32_32x32x16_bf16 v[16:31], v[88:91], v[164:167], v[16:31]
	ds_read_b128 v[48:51], v221 offset:35904
	s_waitcnt vmcnt(2)
	ds_write_b128 v197, v[148:151]
	s_and_saveexec_b64 s[44:45], s[8:9]
	ds_write_b128 v217, v[112:115]
	s_or_b64 exec, exec, s[44:45]
	s_add_i32 s29, s29, 2
	s_min_u32 s2, s29, 27
	s_mul_i32 s2, s2, 0x18000
	s_add_u32 s2, s80, s2
	s_addc_u32 s24, s81, 0
	s_add_u32 s44, s2, 0x60000
	s_addc_u32 s45, s24, 0
	v_lshl_add_u64 v[80:81], s[44:45], 0, v[202:203]
	s_waitcnt lgkmcnt(3)
	v_mfma_f32_32x32x16_bf16 v[0:15], v[52:55], v[160:163], v[0:15]
	ds_read_b128 v[56:59], v221 offset:40512
	v_max3_f32 v52, v96, s96, v64
	v_max3_f32 v52, v52, v97, v65
	v_max3_f32 v82, v52, v98, v66
	ds_write_b128 v219, v[144:147] offset:26624
	s_waitcnt lgkmcnt(4)
	v_mfma_f32_32x32x16_bf16 v[16:31], v[60:63], v[160:163], v[16:31]
	v_max3_f32 v60, v82, v99, v67
	v_max3_f32 v60, v60, v100, v68
	v_max3_f32 v60, v60, v101, v69
	ds_read_b128 v[52:55], v221 offset:35936
	global_load_dwordx4 v[148:151], v[80:81], off
	s_and_saveexec_b64 s[46:47], s[8:9]
	s_cbranch_execz .LBB0_182
	v_lshl_add_u64 v[62:63], s[44:45], 0, v[204:205]
	global_load_dwordx4 v[112:115], v[62:63], off

.LBB0_187:
	v_exp_f32_e32 v52, v96
	v_exp_f32_e32 v53, v97
	v_exp_f32_e32 v56, v98
	v_exp_f32_e32 v57, v99
	v_add_f32_e32 v54, 0, v52
	v_add_f32_e32 v55, 0, v53
	v_cvt_pk_bf16_f32 v164, v52, v53
	ds_read_b128 v[160:163], v220 offset:6656
	ds_read_b128 v[48:51], v220
	ds_read_b128 v[168:171], v220 offset:32
	v_cvt_pk_bf16_f32 v165, v56, v57
	v_add_f32_e32 v52, v56, v54
	v_add_f32_e32 v53, v57, v55
	v_exp_f32_e32 v54, v100
	v_exp_f32_e32 v55, v101
	s_nop 0
	v_add_f32_e32 v52, v54, v52
	v_add_f32_e32 v53, v55, v53
	v_cvt_pk_bf16_f32 v166, v54, v55
	s_waitcnt lgkmcnt(1)
	v_mfma_f32_32x32x16_bf16 v[80:95], v[48:51], v[120:123], v[32:47]
	v_exp_f32_e32 v54, v102
	v_exp_f32_e32 v55, v103
	ds_read_b128 v[96:99], v220 offset:6688
	v_add_f32_e32 v172, v54, v52
	v_add_f32_e32 v173, v55, v53
	v_cvt_pk_bf16_f32 v167, v54, v55
	v_mfma_f32_32x32x16_bf16 v[48:63], v[160:163], v[120:123], v[32:47]
	v_exp_f32_e32 v105, v105
	v_exp_f32_e32 v104, v104
	ds_read_b128 v[100:103], v220 offset:64
	v_add_f32_e32 v162, v105, v173
	v_add_f32_e32 v161, v104, v172
	v_cvt_pk_bf16_f32 v160, v104, v105
	s_waitcnt lgkmcnt(2)
	v_mfma_f32_32x32x16_bf16 v[80:95], v[168:171], v[124:127], v[80:95]
	ds_read_b128 v[172:175], v220 offset:6720
	v_exp_f32_e32 v104, v107
	v_exp_f32_e32 v105, v106
	v_add_f32_e32 v162, v104, v162
	v_add_f32_e32 v163, v105, v161
	v_cvt_pk_bf16_f32 v161, v105, v104
	s_waitcnt lgkmcnt(2)
	v_mfma_f32_32x32x16_bf16 v[48:63], v[96:99], v[124:127], v[48:63]
	v_exp_f32_e32 v96, v109
	v_exp_f32_e32 v97, v108
	ds_read_b128 v[104:107], v220 offset:96
	v_add_f32_e32 v109, v96, v162
	v_add_f32_e32 v108, v97, v163
	v_cvt_pk_bf16_f32 v162, v97, v96
	s_waitcnt lgkmcnt(2)
	v_mfma_f32_32x32x16_bf16 v[80:95], v[100:103], v[128:131], v[80:95]
	v_exp_f32_e32 v110, v110
	v_exp_f32_e32 v111, v111
	ds_read_b128 v[96:99], v220 offset:6752
	v_add_f32_e32 v108, v110, v108
	v_add_f32_e32 v109, v111, v109
	v_cvt_pk_bf16_f32 v163, v110, v111
	s_waitcnt lgkmcnt(2)
	v_mfma_f32_32x32x16_bf16 v[48:63], v[172:175], v[128:131], v[48:63]
	v_exp_f32_e32 v65, v65
	v_exp_f32_e32 v64, v64
	ds_read_b128 v[100:103], v220 offset:128
	v_add_f32_e32 v169, v65, v109
	v_add_f32_e32 v168, v64, v108
	v_cvt_pk_bf16_f32 v172, v64, v65
	s_waitcnt lgkmcnt(2)
	v_mfma_f32_32x32x16_bf16 v[80:95], v[104:107], v[132:135], v[80:95]
	v_exp_f32_e32 v64, v67
	v_exp_f32_e32 v65, v66
	ds_read_b128 v[108:111], v220 offset:6784
	v_add_f32_e32 v105, v64, v169
	v_add_f32_e32 v104, v65, v168
	v_cvt_pk_bf16_f32 v173, v65, v64
	s_waitcnt lgkmcnt(2)
	v_mfma_f32_32x32x16_bf16 v[48:63], v[96:99], v[132:135], v[48:63]
	ds_read_b128 v[64:67], v220 offset:160
	v_exp_f32_e32 v69, v69
	v_exp_f32_e32 v68, v68
	v_add_f32_e32 v105, v69, v105
	v_add_f32_e32 v104, v68, v104
	v_cvt_pk_bf16_f32 v174, v68, v69
	s_waitcnt lgkmcnt(2)
	v_mfma_f32_32x32x16_bf16 v[80:95], v[100:103], v[136:139], v[80:95]
	ds_read_b128 v[96:99], v220 offset:6816
	v_exp_f32_e32 v68, v71
	v_exp_f32_e32 v69, v70
	v_add_f32_e32 v71, v68, v105
	v_add_f32_e32 v70, v69, v104
	v_cvt_pk_bf16_f32 v175, v69, v68
	s_waitcnt lgkmcnt(2)
	v_mfma_f32_32x32x16_bf16 v[48:63], v[108:111], v[136:139], v[48:63]
	v_exp_f32_e32 v68, v73
	v_exp_f32_e32 v69, v72
	ds_read_b128 v[100:103], v221 offset:26624
	v_add_f32_e32 v71, v68, v71
	v_add_f32_e32 v70, v69, v70
	v_cvt_pk_bf16_f32 v168, v69, v68
	s_waitcnt lgkmcnt(2)
	v_mfma_f32_32x32x16_bf16 v[80:95], v[64:67], v[140:143], v[80:95]
	v_exp_f32_e32 v64, v75
	v_exp_f32_e32 v65, v74
	ds_read_b128 v[104:107], v221 offset:31232
	v_add_f32_e32 v67, v64, v71
	v_add_f32_e32 v66, v65, v70
	v_cvt_pk_bf16_f32 v169, v65, v64
	s_waitcnt lgkmcnt(2)
	v_mfma_f32_32x32x16_bf16 v[48:63], v[96:99], v[140:143], v[48:63]
	ds_read_b128 v[68:71], v221 offset:26656
	v_exp_f32_e32 v64, v77
	v_exp_f32_e32 v65, v76
	v_add_f32_e32 v67, v64, v67
	v_add_f32_e32 v66, v65, v66
	v_cvt_pk_bf16_f32 v170, v65, v64
	s_waitcnt lgkmcnt(2)
	v_mfma_f32_32x32x16_bf16 v[0:15], v[100:103], v[176:179], v[0:15]
	v_exp_f32_e32 v64, v78
	v_exp_f32_e32 v65, v79
	ds_read_b128 v[76:79], v221 offset:31264
	v_add_f32_e32 v96, v64, v66
	v_add_f32_e32 v97, v65, v67
	v_cvt_pk_bf16_f32 v171, v64, v65
	s_waitcnt lgkmcnt(2)
	v_mfma_f32_32x32x16_bf16 v[16:31], v[104:107], v[176:179], v[16:31]
	ds_read_b128 v[64:67], v221 offset:26688
	s_waitcnt vmcnt(2)
	ds_write_b128 v197, v[152:155] offset:13312
	s_and_saveexec_b64 s[44:45], s[8:9]
	ds_write_b128 v217, v[116:119] offset:13312
	s_or_b64 exec, exec, s[44:45]
	s_min_u32 s2, s29, 26
	s_mul_i32 s2, s2, 0x18000
	s_add_u32 s2, s80, s2
	s_addc_u32 s24, s81, 0
	s_add_u32 s44, s2, 0x78000
	s_addc_u32 s45, s24, 0
	v_lshl_add_u64 v[98:99], s[44:45], 0, v[202:203]
	s_waitcnt lgkmcnt(3)
	v_mfma_f32_32x32x16_bf16 v[0:15], v[68:71], v[180:183], v[0:15]
	ds_read_b128 v[72:75], v221 offset:31296
	v_max3_f32 v68, v80, s96, v48
	v_max3_f32 v68, v68, v81, v49
	v_max3_f32 v100, v68, v82, v50
	ds_write_b128 v219, v[156:159] offset:35840
	s_waitcnt lgkmcnt(4)
	v_mfma_f32_32x32x16_bf16 v[16:31], v[76:79], v[180:183], v[16:31]
	v_max3_f32 v76, v100, v83, v51
	v_max3_f32 v76, v76, v84, v52
	v_max3_f32 v76, v76, v85, v53
	ds_read_b128 v[68:71], v221 offset:26720
	global_load_dwordx4 v[152:155], v[98:99], off
	s_and_saveexec_b64 s[46:47], s[8:9]
	s_cbranch_execz .LBB0_191
	v_lshl_add_u64 v[78:79], s[44:45], 0, v[204:205]
	global_load_dwordx4 v[116:119], v[78:79], off

; #define LAS __attribute__((address_space(3)))
; __device__ __forceinline__ void p0_prologue(Frame& F, const Args& A, unsigned char* ws) {
;     ...
;         LAS float* cs = (LAS float*)F.lds;
;         const float* c = uni(A.in[1]);
;         float* mod = (float*)(ws + WS_MOD);
;         for (int it = F.vcu; it < DEPTH * (NMODC / 64); it += F.G) {
;             for (int idx = F.tid; idx < 32 * 1024; idx += NTHR) { const int k = idx >> 5, b = idx & 31; const float v = c[b * 1024 + k]; cs[idx] = v / (1.0f + __expf(-v)); }
;             __syncthreads();
.LBB0_926:
	s_and_saveexec_b64 s[10:11], s[6:7]
	s_cbranch_execz .LBB0_929
	v_lshrrev_b32_e32 v13, 5, v196
	v_and_b32_e32 v14, 0x7c00, v52
	v_add_u32_e32 v14, v14, v13
	v_mov_b32_e32 v15, 0
	v_lshl_add_u64 v[20:21], v[14:15], 2, s[8:9]
	v_mov_b32_e32 v22, v51
	s_mov_b32 s12, 0
	global_load_dword v54, v[20:21], off
	global_load_dword v55, v[20:21], off offset:64
	global_load_dword v56, v[20:21], off offset:128
	global_load_dword v57, v[20:21], off offset:192
	global_load_dword v58, v[20:21], off offset:256
	global_load_dword v59, v[20:21], off offset:320
	global_load_dword v60, v[20:21], off offset:384
	global_load_dword v61, v[20:21], off offset:448
.Lcs_fill_loop:
	global_load_dword v62, v[20:21], off offset:512
	global_load_dword v63, v[20:21], off offset:576
	global_load_dword v64, v[20:21], off offset:640
	global_load_dword v65, v[20:21], off offset:704
	global_load_dword v66, v[20:21], off offset:768
	global_load_dword v67, v[20:21], off offset:832
	global_load_dword v68, v[20:21], off offset:896
	global_load_dword v69, v[20:21], off offset:960
	s_waitcnt vmcnt(15)
	v_mul_f32_e32 v14, 0xbfb8aa3b, v54
	v_exp_f32_e32 v14, v14
	s_nop 0
	v_add_f32_e32 v14, 1.0, v14
	v_div_scale_f32 v15, s[14:15], v14, v14, v54
	v_rcp_f32_e32 v16, v15
	v_div_scale_f32 v17, vcc, v54, v14, v54
	v_fma_f32 v18, -v15, v16, 1.0
	v_fmac_f32_e32 v16, v18, v16
	v_mul_f32_e32 v18, v17, v16
	v_fma_f32 v19, -v15, v18, v17
	v_fmac_f32_e32 v18, v19, v16
	v_fma_f32 v15, -v15, v18, v17
	v_div_fmas_f32 v15, v15, v16, v18
	v_div_fixup_f32 v13, v15, v14, v54
	ds_write_b32 v22, v13
	s_waitcnt vmcnt(14)
	v_mul_f32_e32 v14, 0xbfb8aa3b, v55
	v_exp_f32_e32 v14, v14
	s_nop 0
	v_add_f32_e32 v14, 1.0, v14
	v_div_scale_f32 v15, s[14:15], v14, v14, v55
	v_rcp_f32_e32 v16, v15
	v_div_scale_f32 v17, vcc, v55, v14, v55
	v_fma_f32 v18, -v15, v16, 1.0
	v_fmac_f32_e32 v16, v18, v16
	v_mul_f32_e32 v18, v17, v16
	v_fma_f32 v19, -v15, v18, v17
	v_fmac_f32_e32 v18, v19, v16
	v_fma_f32 v15, -v15, v18, v17
	v_div_fmas_f32 v15, v15, v16, v18
	v_div_fixup_f32 v13, v15, v14, v55
	ds_write_b32 v22, v13 offset:2048
	s_waitcnt vmcnt(13)
	v_mul_f32_e32 v14, 0xbfb8aa3b, v56
	v_exp_f32_e32 v14, v14
	s_nop 0
	v_add_f32_e32 v14, 1.0, v14
	v_div_scale_f32 v15, s[14:15], v14, v14, v56
	v_rcp_f32_e32 v16, v15
	v_div_scale_f32 v17, vcc, v56, v14, v56
	v_fma_f32 v18, -v15, v16, 1.0
	v_fmac_f32_e32 v16, v18, v16
	v_mul_f32_e32 v18, v17, v16
	v_fma_f32 v19, -v15, v18, v17
	v_fmac_f32_e32 v18, v19, v16
	v_fma_f32 v15, -v15, v18, v17
	v_div_fmas_f32 v15, v15, v16, v18
	v_div_fixup_f32 v13, v15, v14, v56
	ds_write_b32 v22, v13 offset:4096
	s_waitcnt vmcnt(12)
	v_mul_f32_e32 v14, 0xbfb8aa3b, v57
	v_exp_f32_e32 v14, v14
	s_nop 0
	v_add_f32_e32 v14, 1.0, v14
	v_div_scale_f32 v15, s[14:15], v14, v14, v57
	v_rcp_f32_e32 v16, v15
	v_div_scale_f32 v17, vcc, v57, v14, v57
	v_fma_f32 v18, -v15, v16, 1.0
	v_fmac_f32_e32 v16, v18, v16
	v_mul_f32_e32 v18, v17, v16
	v_fma_f32 v19, -v15, v18, v17
	v_fmac_f32_e32 v18, v19, v16
	v_fma_f32 v15, -v15, v18, v17
	v_div_fmas_f32 v15, v15, v16, v18
	v_div_fixup_f32 v13, v15, v14, v57
	ds_write_b32 v22, v13 offset:6144
	s_waitcnt vmcnt(11)
	v_mul_f32_e32 v14, 0xbfb8aa3b, v58
	v_exp_f32_e32 v14, v14
	s_nop 0
	v_add_f32_e32 v14, 1.0, v14
	v_div_scale_f32 v15, s[14:15], v14, v14, v58
	v_rcp_f32_e32 v16, v15
	v_div_scale_f32 v17, vcc, v58, v14, v58
	v_fma_f32 v18, -v15, v16, 1.0
	v_fmac_f32_e32 v16, v18, v16
	v_mul_f32_e32 v18, v17, v16
	v_fma_f32 v19, -v15, v18, v17
	v_fmac_f32_e32 v18, v19, v16
	v_fma_f32 v15, -v15, v18, v17
	v_div_fmas_f32 v15, v15, v16, v18
	v_div_fixup_f32 v13, v15, v14, v58
	ds_write_b32 v22, v13 offset:8192
	s_waitcnt vmcnt(10)
	v_mul_f32_e32 v14, 0xbfb8aa3b, v59
	v_exp_f32_e32 v14, v14
	s_nop 0
	v_add_f32_e32 v14, 1.0, v14
	v_div_scale_f32 v15, s[14:15], v14, v14, v59
	v_rcp_f32_e32 v16, v15
	v_div_scale_f32 v17, vcc, v59, v14, v59
	v_fma_f32 v18, -v15, v16, 1.0
	v_fmac_f32_e32 v16, v18, v16
	v_mul_f32_e32 v18, v17, v16
	v_fma_f32 v19, -v15, v18, v17
	v_fmac_f32_e32 v18, v19, v16
	v_fma_f32 v15, -v15, v18, v17
	v_div_fmas_f32 v15, v15, v16, v18
	v_div_fixup_f32 v13, v15, v14, v59
	ds_write_b32 v22, v13 offset:10240
	s_waitcnt vmcnt(9)
	v_mul_f32_e32 v14, 0xbfb8aa3b, v60
	v_exp_f32_e32 v14, v14
	s_nop 0
	v_add_f32_e32 v14, 1.0, v14
	v_div_scale_f32 v15, s[14:15], v14, v14, v60
	v_rcp_f32_e32 v16, v15
	v_div_scale_f32 v17, vcc, v60, v14, v60
	v_fma_f32 v18, -v15, v16, 1.0
	v_fmac_f32_e32 v16, v18, v16
	v_mul_f32_e32 v18, v17, v16
	v_fma_f32 v19, -v15, v18, v17
	v_fmac_f32_e32 v18, v19, v16
	v_fma_f32 v15, -v15, v18, v17
	v_div_fmas_f32 v15, v15, v16, v18
	v_div_fixup_f32 v13, v15, v14, v60
	ds_write_b32 v22, v13 offset:12288
	s_waitcnt vmcnt(8)
	v_mul_f32_e32 v14, 0xbfb8aa3b, v61
	v_exp_f32_e32 v14, v14
	s_nop 0
	v_add_f32_e32 v14, 1.0, v14
	v_div_scale_f32 v15, s[14:15], v14, v14, v61
	v_rcp_f32_e32 v16, v15
	v_div_scale_f32 v17, vcc, v61, v14, v61
	v_fma_f32 v18, -v15, v16, 1.0
	v_fmac_f32_e32 v16, v18, v16
	v_mul_f32_e32 v18, v17, v16
	v_fma_f32 v19, -v15, v18, v17
	v_fmac_f32_e32 v18, v19, v16
	v_fma_f32 v15, -v15, v18, v17
	v_div_fmas_f32 v15, v15, v16, v18
	v_div_fixup_f32 v13, v15, v14, v61
	ds_write_b32 v22, v13 offset:14336
	s_add_i32 s12, s12, 1
	s_cmp_lt_u32 s12, 4
	s_cbranch_scc0 .Lcs_fill_last
; __device__ __forceinline__ void p0_prologue(Frame& F, const Args& A, unsigned char* ws) {
;     ...
;             for (int idx = F.tid; idx < 32 * 1024; idx += NTHR) { const int k = idx >> 5, b = idx & 31; const float v = c[b * 1024 + k]; cs[idx] = v / (1.0f + __expf(-v)); }
	v_add_co_u32_e32 v20, vcc, 0x400, v20
	s_nop 1
	v_addc_co_u32_e32 v21, vcc, 0, v21, vcc
	global_load_dword v54, v[20:21], off
	global_load_dword v55, v[20:21], off offset:64
	global_load_dword v56, v[20:21], off offset:128
	global_load_dword v57, v[20:21], off offset:192
	global_load_dword v58, v[20:21], off offset:256
	global_load_dword v59, v[20:21], off offset:320
	global_load_dword v60, v[20:21], off offset:384
	global_load_dword v61, v[20:21], off offset:448
	s_waitcnt vmcnt(15)
	v_mul_f32_e32 v14, 0xbfb8aa3b, v62
	v_exp_f32_e32 v14, v14
	s_nop 0
	v_add_f32_e32 v14, 1.0, v14
	v_div_scale_f32 v15, s[14:15], v14, v14, v62
	v_rcp_f32_e32 v16, v15
	v_div_scale_f32 v17, vcc, v62, v14, v62
	v_fma_f32 v18, -v15, v16, 1.0
	v_fmac_f32_e32 v16, v18, v16
	v_mul_f32_e32 v18, v17, v16
	v_fma_f32 v19, -v15, v18, v17
	v_fmac_f32_e32 v18, v19, v16
	v_fma_f32 v15, -v15, v18, v17
	v_div_fmas_f32 v15, v15, v16, v18
	v_div_fixup_f32 v13, v15, v14, v62
	ds_write_b32 v22, v13 offset:16384
	s_waitcnt vmcnt(14)
	v_mul_f32_e32 v14, 0xbfb8aa3b, v63
	v_exp_f32_e32 v14, v14
	s_nop 0
	v_add_f32_e32 v14, 1.0, v14
	v_div_scale_f32 v15, s[14:15], v14, v14, v63
	v_rcp_f32_e32 v16, v15
	v_div_scale_f32 v17, vcc, v63, v14, v63
	v_fma_f32 v18, -v15, v16, 1.0
	v_fmac_f32_e32 v16, v18, v16
	v_mul_f32_e32 v18, v17, v16
	v_fma_f32 v19, -v15, v18, v17
	v_fmac_f32_e32 v18, v19, v16
	v_fma_f32 v15, -v15, v18, v17
	v_div_fmas_f32 v15, v15, v16, v18
	v_div_fixup_f32 v13, v15, v14, v63
	ds_write_b32 v22, v13 offset:18432
	s_waitcnt vmcnt(13)
	v_mul_f32_e32 v14, 0xbfb8aa3b, v64
	v_exp_f32_e32 v14, v14
	s_nop 0
	v_add_f32_e32 v14, 1.0, v14
	v_div_scale_f32 v15, s[14:15], v14, v14, v64
	v_rcp_f32_e32 v16, v15
	v_div_scale_f32 v17, vcc, v64, v14, v64
	v_fma_f32 v18, -v15, v16, 1.0
	v_fmac_f32_e32 v16, v18, v16
	v_mul_f32_e32 v18, v17, v16
	v_fma_f32 v19, -v15, v18, v17
	v_fmac_f32_e32 v18, v19, v16
	v_fma_f32 v15, -v15, v18, v17
	v_div_fmas_f32 v15, v15, v16, v18
	v_div_fixup_f32 v13, v15, v14, v64
	ds_write_b32 v22, v13 offset:20480
	s_waitcnt vmcnt(12)
	v_mul_f32_e32 v14, 0xbfb8aa3b, v65
	v_exp_f32_e32 v14, v14
	s_nop 0
	v_add_f32_e32 v14, 1.0, v14
	v_div_scale_f32 v15, s[14:15], v14, v14, v65
	v_rcp_f32_e32 v16, v15
	v_div_scale_f32 v17, vcc, v65, v14, v65
	v_fma_f32 v18, -v15, v16, 1.0
	v_fmac_f32_e32 v16, v18, v16
	v_mul_f32_e32 v18, v17, v16
	v_fma_f32 v19, -v15, v18, v17
	v_fmac_f32_e32 v18, v19, v16
	v_fma_f32 v15, -v15, v18, v17
	v_div_fmas_f32 v15, v15, v16, v18
	v_div_fixup_f32 v13, v15, v14, v65
	ds_write_b32 v22, v13 offset:22528
	s_waitcnt vmcnt(11)
	v_mul_f32_e32 v14, 0xbfb8aa3b, v66
	v_exp_f32_e32 v14, v14
	s_nop 0
	v_add_f32_e32 v14, 1.0, v14
	v_div_scale_f32 v15, s[14:15], v14, v14, v66
	v_rcp_f32_e32 v16, v15
	v_div_scale_f32 v17, vcc, v66, v14, v66
	v_fma_f32 v18, -v15, v16, 1.0
	v_fmac_f32_e32 v16, v18, v16
	v_mul_f32_e32 v18, v17, v16
	v_fma_f32 v19, -v15, v18, v17
	v_fmac_f32_e32 v18, v19, v16
	v_fma_f32 v15, -v15, v18, v17
	v_div_fmas_f32 v15, v15, v16, v18
	v_div_fixup_f32 v13, v15, v14, v66
	ds_write_b32 v22, v13 offset:24576
	s_waitcnt vmcnt(10)
	v_mul_f32_e32 v14, 0xbfb8aa3b, v67
	v_exp_f32_e32 v14, v14
	s_nop 0
	v_add_f32_e32 v14, 1.0, v14
	v_div_scale_f32 v15, s[14:15], v14, v14, v67
	v_rcp_f32_e32 v16, v15
	v_div_scale_f32 v17, vcc, v67, v14, v67
	v_fma_f32 v18, -v15, v16, 1.0
	v_fmac_f32_e32 v16, v18, v16
	v_mul_f32_e32 v18, v17, v16
	v_fma_f32 v19, -v15, v18, v17
	v_fmac_f32_e32 v18, v19, v16
	v_fma_f32 v15, -v15, v18, v17
	v_div_fmas_f32 v15, v15, v16, v18
	v_div_fixup_f32 v13, v15, v14, v67
	ds_write_b32 v22, v13 offset:26624
	s_waitcnt vmcnt(9)
	v_mul_f32_e32 v14, 0xbfb8aa3b, v68
	v_exp_f32_e32 v14, v14
	s_nop 0
	v_add_f32_e32 v14, 1.0, v14
	v_div_scale_f32 v15, s[14:15], v14, v14, v68
	v_rcp_f32_e32 v16, v15
	v_div_scale_f32 v17, vcc, v68, v14, v68
	v_fma_f32 v18, -v15, v16, 1.0
	v_fmac_f32_e32 v16, v18, v16
	v_mul_f32_e32 v18, v17, v16
	v_fma_f32 v19, -v15, v18, v17
	v_fmac_f32_e32 v18, v19, v16
	v_fma_f32 v15, -v15, v18, v17
	v_div_fmas_f32 v15, v15, v16, v18
	v_div_fixup_f32 v13, v15, v14, v68
	ds_write_b32 v22, v13 offset:28672
	s_waitcnt vmcnt(8)
	v_mul_f32_e32 v14, 0xbfb8aa3b, v69
	v_exp_f32_e32 v14, v14
	s_nop 0
	v_add_f32_e32 v14, 1.0, v14
	v_div_scale_f32 v15, s[14:15], v14, v14, v69
	v_rcp_f32_e32 v16, v15
	v_div_scale_f32 v17, vcc, v69, v14, v69
	v_fma_f32 v18, -v15, v16, 1.0
	v_fmac_f32_e32 v16, v18, v16
	v_mul_f32_e32 v18, v17, v16
	v_fma_f32 v19, -v15, v18, v17
	v_fmac_f32_e32 v18, v19, v16
	v_fma_f32 v15, -v15, v18, v17
	v_div_fmas_f32 v15, v15, v16, v18
	v_div_fixup_f32 v13, v15, v14, v69
	ds_write_b32 v22, v13 offset:30720
	v_add_u32_e32 v22, 0x8000, v22
	s_branch .Lcs_fill_loop
; __device__ __forceinline__ void p0_prologue(Frame& F, const Args& A, unsigned char* ws) {
;     ...
;             for (int idx = F.tid; idx < 32 * 1024; idx += NTHR) { const int k = idx >> 5, b = idx & 31; const float v = c[b * 1024 + k]; cs[idx] = v / (1.0f + __expf(-v)); }
;             __syncthreads();
.Lcs_fill_last:
	s_waitcnt vmcnt(7)
	v_mul_f32_e32 v14, 0xbfb8aa3b, v62
	v_exp_f32_e32 v14, v14
	s_nop 0
	v_add_f32_e32 v14, 1.0, v14
	v_div_scale_f32 v15, s[14:15], v14, v14, v62
	v_rcp_f32_e32 v16, v15
	v_div_scale_f32 v17, vcc, v62, v14, v62
	v_fma_f32 v18, -v15, v16, 1.0
	v_fmac_f32_e32 v16, v18, v16
	v_mul_f32_e32 v18, v17, v16
	v_fma_f32 v19, -v15, v18, v17
	v_fmac_f32_e32 v18, v19, v16
	v_fma_f32 v15, -v15, v18, v17
	v_div_fmas_f32 v15, v15, v16, v18
	v_div_fixup_f32 v13, v15, v14, v62
	ds_write_b32 v22, v13 offset:16384
	s_waitcnt vmcnt(6)
	v_mul_f32_e32 v14, 0xbfb8aa3b, v63
	v_exp_f32_e32 v14, v14
	s_nop 0
	v_add_f32_e32 v14, 1.0, v14
	v_div_scale_f32 v15, s[14:15], v14, v14, v63
	v_rcp_f32_e32 v16, v15
	v_div_scale_f32 v17, vcc, v63, v14, v63
	v_fma_f32 v18, -v15, v16, 1.0
	v_fmac_f32_e32 v16, v18, v16
	v_mul_f32_e32 v18, v17, v16
	v_fma_f32 v19, -v15, v18, v17
	v_fmac_f32_e32 v18, v19, v16
	v_fma_f32 v15, -v15, v18, v17
	v_div_fmas_f32 v15, v15, v16, v18
	v_div_fixup_f32 v13, v15, v14, v63
	ds_write_b32 v22, v13 offset:18432
	s_waitcnt vmcnt(5)
	v_mul_f32_e32 v14, 0xbfb8aa3b, v64
	v_exp_f32_e32 v14, v14
	s_nop 0
	v_add_f32_e32 v14, 1.0, v14
	v_div_scale_f32 v15, s[14:15], v14, v14, v64
	v_rcp_f32_e32 v16, v15
	v_div_scale_f32 v17, vcc, v64, v14, v64
	v_fma_f32 v18, -v15, v16, 1.0
	v_fmac_f32_e32 v16, v18, v16
	v_mul_f32_e32 v18, v17, v16
	v_fma_f32 v19, -v15, v18, v17
	v_fmac_f32_e32 v18, v19, v16
	v_fma_f32 v15, -v15, v18, v17
	v_div_fmas_f32 v15, v15, v16, v18
	v_div_fixup_f32 v13, v15, v14, v64
	ds_write_b32 v22, v13 offset:20480
	s_waitcnt vmcnt(4)
	v_mul_f32_e32 v14, 0xbfb8aa3b, v65
	v_exp_f32_e32 v14, v14
	s_nop 0
	v_add_f32_e32 v14, 1.0, v14
	v_div_scale_f32 v15, s[14:15], v14, v14, v65
	v_rcp_f32_e32 v16, v15
	v_div_scale_f32 v17, vcc, v65, v14, v65
	v_fma_f32 v18, -v15, v16, 1.0
	v_fmac_f32_e32 v16, v18, v16
	v_mul_f32_e32 v18, v17, v16
	v_fma_f32 v19, -v15, v18, v17
	v_fmac_f32_e32 v18, v19, v16
	v_fma_f32 v15, -v15, v18, v17
	v_div_fmas_f32 v15, v15, v16, v18
	v_div_fixup_f32 v13, v15, v14, v65
	ds_write_b32 v22, v13 offset:22528
	s_waitcnt vmcnt(3)
	v_mul_f32_e32 v14, 0xbfb8aa3b, v66
	v_exp_f32_e32 v14, v14
	s_nop 0
	v_add_f32_e32 v14, 1.0, v14
	v_div_scale_f32 v15, s[14:15], v14, v14, v66
	v_rcp_f32_e32 v16, v15
	v_div_scale_f32 v17, vcc, v66, v14, v66
	v_fma_f32 v18, -v15, v16, 1.0
	v_fmac_f32_e32 v16, v18, v16
	v_mul_f32_e32 v18, v17, v16
	v_fma_f32 v19, -v15, v18, v17
	v_fmac_f32_e32 v18, v19, v16
	v_fma_f32 v15, -v15, v18, v17
	v_div_fmas_f32 v15, v15, v16, v18
	v_div_fixup_f32 v13, v15, v14, v66
	ds_write_b32 v22, v13 offset:24576
	s_waitcnt vmcnt(2)
	v_mul_f32_e32 v14, 0xbfb8aa3b, v67
	v_exp_f32_e32 v14, v14
	s_nop 0
	v_add_f32_e32 v14, 1.0, v14
	v_div_scale_f32 v15, s[14:15], v14, v14, v67
	v_rcp_f32_e32 v16, v15
	v_div_scale_f32 v17, vcc, v67, v14, v67
	v_fma_f32 v18, -v15, v16, 1.0
	v_fmac_f32_e32 v16, v18, v16
	v_mul_f32_e32 v18, v17, v16
	v_fma_f32 v19, -v15, v18, v17
	v_fmac_f32_e32 v18, v19, v16
	v_fma_f32 v15, -v15, v18, v17
	v_div_fmas_f32 v15, v15, v16, v18
	v_div_fixup_f32 v13, v15, v14, v67
	ds_write_b32 v22, v13 offset:26624
	s_waitcnt vmcnt(1)
	v_mul_f32_e32 v14, 0xbfb8aa3b, v68
	v_exp_f32_e32 v14, v14
	s_nop 0
	v_add_f32_e32 v14, 1.0, v14
	v_div_scale_f32 v15, s[14:15], v14, v14, v68
	v_rcp_f32_e32 v16, v15
	v_div_scale_f32 v17, vcc, v68, v14, v68
	v_fma_f32 v18, -v15, v16, 1.0
	v_fmac_f32_e32 v16, v18, v16
	v_mul_f32_e32 v18, v17, v16
	v_fma_f32 v19, -v15, v18, v17
	v_fmac_f32_e32 v18, v19, v16
	v_fma_f32 v15, -v15, v18, v17
	v_div_fmas_f32 v15, v15, v16, v18
	v_div_fixup_f32 v13, v15, v14, v68
	ds_write_b32 v22, v13 offset:28672
	s_waitcnt vmcnt(0)
	v_mul_f32_e32 v14, 0xbfb8aa3b, v69
	v_exp_f32_e32 v14, v14
	s_nop 0
	v_add_f32_e32 v14, 1.0, v14
	v_div_scale_f32 v15, s[14:15], v14, v14, v69
	v_rcp_f32_e32 v16, v15
	v_div_scale_f32 v17, vcc, v69, v14, v69
	v_fma_f32 v18, -v15, v16, 1.0
	v_fmac_f32_e32 v16, v18, v16
	v_mul_f32_e32 v18, v17, v16
	v_fma_f32 v19, -v15, v18, v17
	v_fmac_f32_e32 v18, v19, v16
	v_fma_f32 v15, -v15, v18, v17
	v_div_fmas_f32 v15, v15, v16, v18
	v_div_fixup_f32 v13, v15, v14, v69
	ds_write_b32 v22, v13 offset:30720
.LBB0_929:
	s_or_b64 exec, exec, s[10:11]
	v_mov_b64_e32 v[10:11], s[0:1]
	s_waitcnt lgkmcnt(0)
	s_barrier
; #define LAS __attribute__((address_space(3)))
; __device__ __forceinline__ void p0_prologue(Frame& F, const Args& A, unsigned char* ws) {
;     ...
;             const int l = it / (NMODC / 64), jb = it % (NMODC / 64), col = jb * 64 + F.lane;
;             const float* w = uni(A.in[2]) + (size_t)l * 1024 * NMODC + col;
;             float acc[32];
; #pragma unroll
;             for (int b = 0; b < 32; ++b) acc[b] = 0.f;
;             const int kbeg = F.wave * 128;
; #pragma unroll 4
;             for (int k = kbeg; k < kbeg + 128; ++k) {
;                 const float wv = w[(size_t)k * NMODC];
;                 const LAS f32x4* cr = (const LAS f32x4*)(cs + k * 32);
; #pragma unroll
;                 for (int b4 = 0; b4 < 8; ++b4) { const f32x4 cv = cr[b4]; acc[4 * b4] += cv[0] * wv; acc[4 * b4 + 1] += cv[1] * wv; acc[4 * b4 + 2] += cv[2] * wv; acc[4 * b4 + 3] += cv[3] * wv; }
;             }
	flat_load_dwordx2 v[10:11], v[10:11] offset:16
	s_mul_hi_i32 s12, s33, 0x38e38e39
	s_lshr_b32 s13, s12, 31
	s_ashr_i32 s12, s12, 5
	s_add_i32 s12, s12, s13
	v_lshl_or_b32 v43, s33, 6, v198
	s_ashr_i32 s13, s12, 31
	s_mul_i32 s17, s12, 0x2400
	v_subrev_u32_e32 v44, s17, v43
	s_mul_i32 s16, s12, 0x2400000
	s_mul_hi_i32 s15, s12, 0x2400000
	v_mov_b32_e32 v12, 0
	v_ashrrev_i32_e32 v45, 31, v44
	s_mov_b64 s[10:11], 0
	s_mov_b32 s14, s5
	v_mov_b32_e32 v13, v12
	v_mov_b32_e32 v14, v12
	v_mov_b32_e32 v15, v12
	v_mov_b32_e32 v16, v12
	v_mov_b32_e32 v17, v12
	v_mov_b32_e32 v18, v12
	v_mov_b32_e32 v19, v12
	v_mov_b32_e32 v20, v12
	v_mov_b32_e32 v21, v12
	v_mov_b32_e32 v22, v12
	v_mov_b32_e32 v23, v12
	v_mov_b32_e32 v24, v12
	v_mov_b32_e32 v25, v12
	v_mov_b32_e32 v26, v12
	v_mov_b32_e32 v27, v12
	v_mov_b32_e32 v28, v12
	v_mov_b32_e32 v29, v12
	v_mov_b32_e32 v30, v12
	v_mov_b32_e32 v31, v12
	v_mov_b32_e32 v32, v12
	v_mov_b32_e32 v33, v12
	v_mov_b32_e32 v34, v12
	v_mov_b32_e32 v35, v12
	v_mov_b32_e32 v36, v12
	v_mov_b32_e32 v37, v12
	v_mov_b32_e32 v38, v12
	v_mov_b32_e32 v39, v12
	v_mov_b32_e32 v40, v12
	v_mov_b32_e32 v41, v12
	v_mov_b32_e32 v42, v12
	v_mov_b32_e32 v43, v12
	s_waitcnt vmcnt(0) lgkmcnt(0)
	v_readfirstlane_b32 s18, v10
	v_readfirstlane_b32 s17, v11
	s_add_u32 s18, s18, s2
	s_addc_u32 s17, s17, s4
	s_add_u32 s16, s18, s16
	s_addc_u32 s17, s17, s15
	v_lshl_add_u64 v[10:11], v[44:45], 2, s[16:17]
	s_mov_b32 s17, 0
	s_mov_b32 s16, 0x0
	v_lshl_add_u64 v[130:131], v[10:11], 0, s[16:17]
	global_load_dword v188, v[130:131], off
	s_add_u32 s16, s16, 0x9000
	v_lshl_add_u64 v[130:131], v[10:11], 0, s[16:17]
	global_load_dword v190, v[130:131], off
	s_add_u32 s16, s16, 0x9000
	v_lshl_add_u64 v[130:131], v[10:11], 0, s[16:17]
	global_load_dword v200, v[130:131], off
	s_add_u32 s16, s16, 0x9000
	v_lshl_add_u64 v[130:131], v[10:11], 0, s[16:17]
	global_load_dword v202, v[130:131], off
	s_mov_b32 s16, 0x24000
	v_lshl_add_u64 v[130:131], v[10:11], 0, s[16:17]
	global_load_dword v204, v[130:131], off
	s_add_u32 s16, s16, 0x9000
	v_lshl_add_u64 v[130:131], v[10:11], 0, s[16:17]
	global_load_dword v206, v[130:131], off
	s_add_u32 s16, s16, 0x9000
	v_lshl_add_u64 v[130:131], v[10:11], 0, s[16:17]
	global_load_dword v208, v[130:131], off
	s_add_u32 s16, s16, 0x9000
	v_lshl_add_u64 v[130:131], v[10:11], 0, s[16:17]
	global_load_dword v210, v[130:131], off
	s_mov_b32 s16, 0x48000
	v_lshl_add_u64 v[130:131], v[10:11], 0, s[16:17]
	global_load_dword v212, v[130:131], off
	s_add_u32 s16, s16, 0x9000
	v_lshl_add_u64 v[130:131], v[10:11], 0, s[16:17]
	global_load_dword v214, v[130:131], off
	s_add_u32 s16, s16, 0x9000
	v_lshl_add_u64 v[130:131], v[10:11], 0, s[16:17]
	global_load_dword v216, v[130:131], off
	s_add_u32 s16, s16, 0x9000
	v_lshl_add_u64 v[130:131], v[10:11], 0, s[16:17]
	global_load_dword v218, v[130:131], off
	s_mov_b32 s16, 0x6c000
	v_lshl_add_u64 v[130:131], v[10:11], 0, s[16:17]
	global_load_dword v220, v[130:131], off
	s_add_u32 s16, s16, 0x9000
	v_lshl_add_u64 v[130:131], v[10:11], 0, s[16:17]
	global_load_dword v222, v[130:131], off
	s_add_u32 s16, s16, 0x9000
	v_lshl_add_u64 v[130:131], v[10:11], 0, s[16:17]
	global_load_dword v234, v[130:131], off
	s_add_u32 s16, s16, 0x9000
	v_lshl_add_u64 v[130:131], v[10:11], 0, s[16:17]
	global_load_dword v236, v[130:131], off
.Ladaln_k_loop:
	v_mov_b32_e32 v53, s14
	ds_read_b128 v[54:57], v53
	ds_read_b128 v[58:61], v53 offset:16
	ds_read_b128 v[62:65], v53 offset:32
	ds_read_b128 v[66:69], v53 offset:48
	ds_read_b128 v[70:73], v53 offset:64
	ds_read_b128 v[74:77], v53 offset:80
	ds_read_b128 v[78:81], v53 offset:96
	ds_read_b128 v[82:85], v53 offset:112
	ds_read_b128 v[86:89], v53 offset:128
	ds_read_b128 v[90:93], v53 offset:144
	ds_read_b128 v[94:97], v53 offset:160
	ds_read_b128 v[98:101], v53 offset:176
	ds_read_b128 v[102:105], v53 offset:192
	ds_read_b128 v[106:109], v53 offset:208
	ds_read_b128 v[110:113], v53 offset:224
	ds_read_b128 v[114:117], v53 offset:240
	ds_read_b128 v[118:121], v53 offset:256
	ds_read_b128 v[122:125], v53 offset:272
	ds_read_b128 v[126:129], v53 offset:288
	ds_read_b128 v[130:133], v53 offset:304
	ds_read_b128 v[134:137], v53 offset:320
	ds_read_b128 v[138:141], v53 offset:336
	ds_read_b128 v[142:145], v53 offset:352
	ds_read_b128 v[146:149], v53 offset:368
	ds_read_b128 v[150:153], v53 offset:384
	ds_read_b128 v[154:157], v53 offset:400
	ds_read_b128 v[158:161], v53 offset:416
	ds_read_b128 v[162:165], v53 offset:432
	ds_read_b128 v[166:169], v53 offset:448
	ds_read_b128 v[170:173], v53 offset:464
	ds_read_b128 v[174:177], v53 offset:480
	ds_read_b128 v[178:181], v53 offset:496
	s_addk_i32 s14, 0x200
	s_waitcnt vmcnt(12)
	s_waitcnt lgkmcnt(0)
; #define LAS __attribute__((address_space(3)))
; __device__ __forceinline__ void p0_prologue(Frame& F, const Args& A, unsigned char* ws) {
;     ...
; #pragma unroll 4
;             for (int k = kbeg; k < kbeg + 128; ++k) {
;                 const float wv = w[(size_t)k * NMODC];
;                 const LAS f32x4* cr = (const LAS f32x4*)(cs + k * 32);
; #pragma unroll
;                 for (int b4 = 0; b4 < 8; ++b4) { const f32x4 cv = cr[b4]; acc[4 * b4] += cv[0] * wv; acc[4 * b4 + 1] += cv[1] * wv; acc[4 * b4 + 2] += cv[2] * wv; acc[4 * b4 + 3] += cv[3] * wv; }
;             }
	v_pk_fma_f32 v[14:15], v[188:189], v[54:55], v[14:15] op_sel_hi:[0,1,1]
	v_pk_fma_f32 v[16:17], v[188:189], v[56:57], v[16:17] op_sel_hi:[0,1,1]
	v_pk_fma_f32 v[18:19], v[188:189], v[58:59], v[18:19] op_sel_hi:[0,1,1]
	v_pk_fma_f32 v[20:21], v[188:189], v[60:61], v[20:21] op_sel_hi:[0,1,1]
	v_pk_fma_f32 v[22:23], v[188:189], v[62:63], v[22:23] op_sel_hi:[0,1,1]
	v_pk_fma_f32 v[24:25], v[188:189], v[64:65], v[24:25] op_sel_hi:[0,1,1]
	v_pk_fma_f32 v[26:27], v[188:189], v[66:67], v[26:27] op_sel_hi:[0,1,1]
	v_pk_fma_f32 v[28:29], v[188:189], v[68:69], v[28:29] op_sel_hi:[0,1,1]
	v_pk_fma_f32 v[30:31], v[188:189], v[70:71], v[30:31] op_sel_hi:[0,1,1]
	v_pk_fma_f32 v[32:33], v[188:189], v[72:73], v[32:33] op_sel_hi:[0,1,1]
	v_pk_fma_f32 v[34:35], v[188:189], v[74:75], v[34:35] op_sel_hi:[0,1,1]
	v_pk_fma_f32 v[36:37], v[188:189], v[76:77], v[36:37] op_sel_hi:[0,1,1]
	v_pk_fma_f32 v[38:39], v[188:189], v[78:79], v[38:39] op_sel_hi:[0,1,1]
	v_pk_fma_f32 v[40:41], v[188:189], v[80:81], v[40:41] op_sel_hi:[0,1,1]
	v_pk_fma_f32 v[42:43], v[188:189], v[82:83], v[42:43] op_sel_hi:[0,1,1]
	v_pk_fma_f32 v[12:13], v[188:189], v[84:85], v[12:13] op_sel_hi:[0,1,1]
	v_pk_fma_f32 v[14:15], v[190:191], v[86:87], v[14:15] op_sel_hi:[0,1,1]
	v_pk_fma_f32 v[16:17], v[190:191], v[88:89], v[16:17] op_sel_hi:[0,1,1]
	v_pk_fma_f32 v[18:19], v[190:191], v[90:91], v[18:19] op_sel_hi:[0,1,1]
	v_pk_fma_f32 v[20:21], v[190:191], v[92:93], v[20:21] op_sel_hi:[0,1,1]
	v_pk_fma_f32 v[22:23], v[190:191], v[94:95], v[22:23] op_sel_hi:[0,1,1]
	v_pk_fma_f32 v[24:25], v[190:191], v[96:97], v[24:25] op_sel_hi:[0,1,1]
	v_pk_fma_f32 v[26:27], v[190:191], v[98:99], v[26:27] op_sel_hi:[0,1,1]
	v_pk_fma_f32 v[28:29], v[190:191], v[100:101], v[28:29] op_sel_hi:[0,1,1]
	v_pk_fma_f32 v[30:31], v[190:191], v[102:103], v[30:31] op_sel_hi:[0,1,1]
	v_pk_fma_f32 v[32:33], v[190:191], v[104:105], v[32:33] op_sel_hi:[0,1,1]
	v_pk_fma_f32 v[34:35], v[190:191], v[106:107], v[34:35] op_sel_hi:[0,1,1]
	v_pk_fma_f32 v[36:37], v[190:191], v[108:109], v[36:37] op_sel_hi:[0,1,1]
	v_pk_fma_f32 v[38:39], v[190:191], v[110:111], v[38:39] op_sel_hi:[0,1,1]
	v_pk_fma_f32 v[40:41], v[190:191], v[112:113], v[40:41] op_sel_hi:[0,1,1]
	v_pk_fma_f32 v[42:43], v[190:191], v[114:115], v[42:43] op_sel_hi:[0,1,1]
	v_pk_fma_f32 v[12:13], v[190:191], v[116:117], v[12:13] op_sel_hi:[0,1,1]
	v_pk_fma_f32 v[14:15], v[200:201], v[118:119], v[14:15] op_sel_hi:[0,1,1]
	v_pk_fma_f32 v[16:17], v[200:201], v[120:121], v[16:17] op_sel_hi:[0,1,1]
	v_pk_fma_f32 v[18:19], v[200:201], v[122:123], v[18:19] op_sel_hi:[0,1,1]
	v_pk_fma_f32 v[20:21], v[200:201], v[124:125], v[20:21] op_sel_hi:[0,1,1]
	v_pk_fma_f32 v[22:23], v[200:201], v[126:127], v[22:23] op_sel_hi:[0,1,1]
	v_pk_fma_f32 v[24:25], v[200:201], v[128:129], v[24:25] op_sel_hi:[0,1,1]
	v_pk_fma_f32 v[26:27], v[200:201], v[130:131], v[26:27] op_sel_hi:[0,1,1]
	v_pk_fma_f32 v[28:29], v[200:201], v[132:133], v[28:29] op_sel_hi:[0,1,1]
	v_pk_fma_f32 v[30:31], v[200:201], v[134:135], v[30:31] op_sel_hi:[0,1,1]
	v_pk_fma_f32 v[32:33], v[200:201], v[136:137], v[32:33] op_sel_hi:[0,1,1]
	v_pk_fma_f32 v[34:35], v[200:201], v[138:139], v[34:35] op_sel_hi:[0,1,1]
	v_pk_fma_f32 v[36:37], v[200:201], v[140:141], v[36:37] op_sel_hi:[0,1,1]
	v_pk_fma_f32 v[38:39], v[200:201], v[142:143], v[38:39] op_sel_hi:[0,1,1]
	v_pk_fma_f32 v[40:41], v[200:201], v[144:145], v[40:41] op_sel_hi:[0,1,1]
	v_pk_fma_f32 v[42:43], v[200:201], v[146:147], v[42:43] op_sel_hi:[0,1,1]
	v_pk_fma_f32 v[12:13], v[200:201], v[148:149], v[12:13] op_sel_hi:[0,1,1]
	v_pk_fma_f32 v[14:15], v[202:203], v[150:151], v[14:15] op_sel_hi:[0,1,1]
	v_pk_fma_f32 v[16:17], v[202:203], v[152:153], v[16:17] op_sel_hi:[0,1,1]
	v_pk_fma_f32 v[18:19], v[202:203], v[154:155], v[18:19] op_sel_hi:[0,1,1]
	v_pk_fma_f32 v[20:21], v[202:203], v[156:157], v[20:21] op_sel_hi:[0,1,1]
	v_pk_fma_f32 v[22:23], v[202:203], v[158:159], v[22:23] op_sel_hi:[0,1,1]
	v_pk_fma_f32 v[24:25], v[202:203], v[160:161], v[24:25] op_sel_hi:[0,1,1]
	v_pk_fma_f32 v[26:27], v[202:203], v[162:163], v[26:27] op_sel_hi:[0,1,1]
	v_pk_fma_f32 v[28:29], v[202:203], v[164:165], v[28:29] op_sel_hi:[0,1,1]
	v_pk_fma_f32 v[30:31], v[202:203], v[166:167], v[30:31] op_sel_hi:[0,1,1]
	v_pk_fma_f32 v[32:33], v[202:203], v[168:169], v[32:33] op_sel_hi:[0,1,1]
	v_pk_fma_f32 v[34:35], v[202:203], v[170:171], v[34:35] op_sel_hi:[0,1,1]
	v_pk_fma_f32 v[36:37], v[202:203], v[172:173], v[36:37] op_sel_hi:[0,1,1]
	v_pk_fma_f32 v[38:39], v[202:203], v[174:175], v[38:39] op_sel_hi:[0,1,1]
	v_pk_fma_f32 v[40:41], v[202:203], v[176:177], v[40:41] op_sel_hi:[0,1,1]
	v_pk_fma_f32 v[42:43], v[202:203], v[178:179], v[42:43] op_sel_hi:[0,1,1]
	v_pk_fma_f32 v[12:13], v[202:203], v[180:181], v[12:13] op_sel_hi:[0,1,1]
	s_add_u32 s16, s10, 0x90000
	s_min_u32 s16, s16, 0x45c000
	v_lshl_add_u64 v[130:131], v[10:11], 0, s[16:17]
	global_load_dword v188, v[130:131], off
	s_add_u32 s16, s16, 0x9000
	v_lshl_add_u64 v[130:131], v[10:11], 0, s[16:17]
	global_load_dword v190, v[130:131], off
	s_add_u32 s16, s16, 0x9000
	v_lshl_add_u64 v[130:131], v[10:11], 0, s[16:17]
	global_load_dword v200, v[130:131], off
	s_add_u32 s16, s16, 0x9000
	v_lshl_add_u64 v[130:131], v[10:11], 0, s[16:17]
	global_load_dword v202, v[130:131], off
	v_mov_b32_e32 v53, s14
	ds_read_b128 v[54:57], v53
	ds_read_b128 v[58:61], v53 offset:16
	ds_read_b128 v[62:65], v53 offset:32
	ds_read_b128 v[66:69], v53 offset:48
	ds_read_b128 v[70:73], v53 offset:64
	ds_read_b128 v[74:77], v53 offset:80
	ds_read_b128 v[78:81], v53 offset:96
	ds_read_b128 v[82:85], v53 offset:112
	ds_read_b128 v[86:89], v53 offset:128
	ds_read_b128 v[90:93], v53 offset:144
	ds_read_b128 v[94:97], v53 offset:160
	ds_read_b128 v[98:101], v53 offset:176
	ds_read_b128 v[102:105], v53 offset:192
	ds_read_b128 v[106:109], v53 offset:208
	ds_read_b128 v[110:113], v53 offset:224
	ds_read_b128 v[114:117], v53 offset:240
	ds_read_b128 v[118:121], v53 offset:256
	ds_read_b128 v[122:125], v53 offset:272
	ds_read_b128 v[126:129], v53 offset:288
	ds_read_b128 v[130:133], v53 offset:304
	ds_read_b128 v[134:137], v53 offset:320
	ds_read_b128 v[138:141], v53 offset:336
	ds_read_b128 v[142:145], v53 offset:352
	ds_read_b128 v[146:149], v53 offset:368
	ds_read_b128 v[150:153], v53 offset:384
	ds_read_b128 v[154:157], v53 offset:400
	ds_read_b128 v[158:161], v53 offset:416
	ds_read_b128 v[162:165], v53 offset:432
	ds_read_b128 v[166:169], v53 offset:448
	ds_read_b128 v[170:173], v53 offset:464
	ds_read_b128 v[174:177], v53 offset:480
	ds_read_b128 v[178:181], v53 offset:496
	s_addk_i32 s14, 0x200
	s_waitcnt vmcnt(12)
; #define LAS __attribute__((address_space(3)))
; __device__ __forceinline__ void p0_prologue(Frame& F, const Args& A, unsigned char* ws) {
;     ...
; #pragma unroll 4
;             for (int k = kbeg; k < kbeg + 128; ++k) {
;                 const float wv = w[(size_t)k * NMODC];
;                 const LAS f32x4* cr = (const LAS f32x4*)(cs + k * 32);
; #pragma unroll
;                 for (int b4 = 0; b4 < 8; ++b4) { const f32x4 cv = cr[b4]; acc[4 * b4] += cv[0] * wv; acc[4 * b4 + 1] += cv[1] * wv; acc[4 * b4 + 2] += cv[2] * wv; acc[4 * b4 + 3] += cv[3] * wv; }
;             }
	s_waitcnt lgkmcnt(0)
	v_pk_fma_f32 v[14:15], v[204:205], v[54:55], v[14:15] op_sel_hi:[0,1,1]
	v_pk_fma_f32 v[16:17], v[204:205], v[56:57], v[16:17] op_sel_hi:[0,1,1]
	v_pk_fma_f32 v[18:19], v[204:205], v[58:59], v[18:19] op_sel_hi:[0,1,1]
	v_pk_fma_f32 v[20:21], v[204:205], v[60:61], v[20:21] op_sel_hi:[0,1,1]
	v_pk_fma_f32 v[22:23], v[204:205], v[62:63], v[22:23] op_sel_hi:[0,1,1]
	v_pk_fma_f32 v[24:25], v[204:205], v[64:65], v[24:25] op_sel_hi:[0,1,1]
	v_pk_fma_f32 v[26:27], v[204:205], v[66:67], v[26:27] op_sel_hi:[0,1,1]
	v_pk_fma_f32 v[28:29], v[204:205], v[68:69], v[28:29] op_sel_hi:[0,1,1]
	v_pk_fma_f32 v[30:31], v[204:205], v[70:71], v[30:31] op_sel_hi:[0,1,1]
	v_pk_fma_f32 v[32:33], v[204:205], v[72:73], v[32:33] op_sel_hi:[0,1,1]
	v_pk_fma_f32 v[34:35], v[204:205], v[74:75], v[34:35] op_sel_hi:[0,1,1]
	v_pk_fma_f32 v[36:37], v[204:205], v[76:77], v[36:37] op_sel_hi:[0,1,1]
	v_pk_fma_f32 v[38:39], v[204:205], v[78:79], v[38:39] op_sel_hi:[0,1,1]
	v_pk_fma_f32 v[40:41], v[204:205], v[80:81], v[40:41] op_sel_hi:[0,1,1]
	v_pk_fma_f32 v[42:43], v[204:205], v[82:83], v[42:43] op_sel_hi:[0,1,1]
	v_pk_fma_f32 v[12:13], v[204:205], v[84:85], v[12:13] op_sel_hi:[0,1,1]
	v_pk_fma_f32 v[14:15], v[206:207], v[86:87], v[14:15] op_sel_hi:[0,1,1]
	v_pk_fma_f32 v[16:17], v[206:207], v[88:89], v[16:17] op_sel_hi:[0,1,1]
	v_pk_fma_f32 v[18:19], v[206:207], v[90:91], v[18:19] op_sel_hi:[0,1,1]
	v_pk_fma_f32 v[20:21], v[206:207], v[92:93], v[20:21] op_sel_hi:[0,1,1]
	v_pk_fma_f32 v[22:23], v[206:207], v[94:95], v[22:23] op_sel_hi:[0,1,1]
	v_pk_fma_f32 v[24:25], v[206:207], v[96:97], v[24:25] op_sel_hi:[0,1,1]
	v_pk_fma_f32 v[26:27], v[206:207], v[98:99], v[26:27] op_sel_hi:[0,1,1]
	v_pk_fma_f32 v[28:29], v[206:207], v[100:101], v[28:29] op_sel_hi:[0,1,1]
	v_pk_fma_f32 v[30:31], v[206:207], v[102:103], v[30:31] op_sel_hi:[0,1,1]
	v_pk_fma_f32 v[32:33], v[206:207], v[104:105], v[32:33] op_sel_hi:[0,1,1]
	v_pk_fma_f32 v[34:35], v[206:207], v[106:107], v[34:35] op_sel_hi:[0,1,1]
	v_pk_fma_f32 v[36:37], v[206:207], v[108:109], v[36:37] op_sel_hi:[0,1,1]
	v_pk_fma_f32 v[38:39], v[206:207], v[110:111], v[38:39] op_sel_hi:[0,1,1]
	v_pk_fma_f32 v[40:41], v[206:207], v[112:113], v[40:41] op_sel_hi:[0,1,1]
	v_pk_fma_f32 v[42:43], v[206:207], v[114:115], v[42:43] op_sel_hi:[0,1,1]
	v_pk_fma_f32 v[12:13], v[206:207], v[116:117], v[12:13] op_sel_hi:[0,1,1]
	v_pk_fma_f32 v[14:15], v[208:209], v[118:119], v[14:15] op_sel_hi:[0,1,1]
	v_pk_fma_f32 v[16:17], v[208:209], v[120:121], v[16:17] op_sel_hi:[0,1,1]
	v_pk_fma_f32 v[18:19], v[208:209], v[122:123], v[18:19] op_sel_hi:[0,1,1]
	v_pk_fma_f32 v[20:21], v[208:209], v[124:125], v[20:21] op_sel_hi:[0,1,1]
	v_pk_fma_f32 v[22:23], v[208:209], v[126:127], v[22:23] op_sel_hi:[0,1,1]
	v_pk_fma_f32 v[24:25], v[208:209], v[128:129], v[24:25] op_sel_hi:[0,1,1]
	v_pk_fma_f32 v[26:27], v[208:209], v[130:131], v[26:27] op_sel_hi:[0,1,1]
	v_pk_fma_f32 v[28:29], v[208:209], v[132:133], v[28:29] op_sel_hi:[0,1,1]
	v_pk_fma_f32 v[30:31], v[208:209], v[134:135], v[30:31] op_sel_hi:[0,1,1]
	v_pk_fma_f32 v[32:33], v[208:209], v[136:137], v[32:33] op_sel_hi:[0,1,1]
	v_pk_fma_f32 v[34:35], v[208:209], v[138:139], v[34:35] op_sel_hi:[0,1,1]
	v_pk_fma_f32 v[36:37], v[208:209], v[140:141], v[36:37] op_sel_hi:[0,1,1]
	v_pk_fma_f32 v[38:39], v[208:209], v[142:143], v[38:39] op_sel_hi:[0,1,1]
	v_pk_fma_f32 v[40:41], v[208:209], v[144:145], v[40:41] op_sel_hi:[0,1,1]
	v_pk_fma_f32 v[42:43], v[208:209], v[146:147], v[42:43] op_sel_hi:[0,1,1]
	v_pk_fma_f32 v[12:13], v[208:209], v[148:149], v[12:13] op_sel_hi:[0,1,1]
	v_pk_fma_f32 v[14:15], v[210:211], v[150:151], v[14:15] op_sel_hi:[0,1,1]
	v_pk_fma_f32 v[16:17], v[210:211], v[152:153], v[16:17] op_sel_hi:[0,1,1]
	v_pk_fma_f32 v[18:19], v[210:211], v[154:155], v[18:19] op_sel_hi:[0,1,1]
	v_pk_fma_f32 v[20:21], v[210:211], v[156:157], v[20:21] op_sel_hi:[0,1,1]
	v_pk_fma_f32 v[22:23], v[210:211], v[158:159], v[22:23] op_sel_hi:[0,1,1]
	v_pk_fma_f32 v[24:25], v[210:211], v[160:161], v[24:25] op_sel_hi:[0,1,1]
	v_pk_fma_f32 v[26:27], v[210:211], v[162:163], v[26:27] op_sel_hi:[0,1,1]
	v_pk_fma_f32 v[28:29], v[210:211], v[164:165], v[28:29] op_sel_hi:[0,1,1]
	v_pk_fma_f32 v[30:31], v[210:211], v[166:167], v[30:31] op_sel_hi:[0,1,1]
	v_pk_fma_f32 v[32:33], v[210:211], v[168:169], v[32:33] op_sel_hi:[0,1,1]
	v_pk_fma_f32 v[34:35], v[210:211], v[170:171], v[34:35] op_sel_hi:[0,1,1]
	v_pk_fma_f32 v[36:37], v[210:211], v[172:173], v[36:37] op_sel_hi:[0,1,1]
	v_pk_fma_f32 v[38:39], v[210:211], v[174:175], v[38:39] op_sel_hi:[0,1,1]
	v_pk_fma_f32 v[40:41], v[210:211], v[176:177], v[40:41] op_sel_hi:[0,1,1]
	v_pk_fma_f32 v[42:43], v[210:211], v[178:179], v[42:43] op_sel_hi:[0,1,1]
	v_pk_fma_f32 v[12:13], v[210:211], v[180:181], v[12:13] op_sel_hi:[0,1,1]
	s_add_u32 s16, s10, 0xb4000
	s_min_u32 s16, s16, 0x45c000
	v_lshl_add_u64 v[130:131], v[10:11], 0, s[16:17]
	global_load_dword v204, v[130:131], off
	s_add_u32 s16, s16, 0x9000
	v_lshl_add_u64 v[130:131], v[10:11], 0, s[16:17]
	global_load_dword v206, v[130:131], off
	s_add_u32 s16, s16, 0x9000
	v_lshl_add_u64 v[130:131], v[10:11], 0, s[16:17]
	global_load_dword v208, v[130:131], off
	s_add_u32 s16, s16, 0x9000
	v_lshl_add_u64 v[130:131], v[10:11], 0, s[16:17]
	global_load_dword v210, v[130:131], off
	v_mov_b32_e32 v53, s14
	ds_read_b128 v[54:57], v53
	ds_read_b128 v[58:61], v53 offset:16
	ds_read_b128 v[62:65], v53 offset:32
	ds_read_b128 v[66:69], v53 offset:48
	ds_read_b128 v[70:73], v53 offset:64
	ds_read_b128 v[74:77], v53 offset:80
	ds_read_b128 v[78:81], v53 offset:96
	ds_read_b128 v[82:85], v53 offset:112
	ds_read_b128 v[86:89], v53 offset:128
	ds_read_b128 v[90:93], v53 offset:144
	ds_read_b128 v[94:97], v53 offset:160
	ds_read_b128 v[98:101], v53 offset:176
	ds_read_b128 v[102:105], v53 offset:192
	ds_read_b128 v[106:109], v53 offset:208
	ds_read_b128 v[110:113], v53 offset:224
	ds_read_b128 v[114:117], v53 offset:240
	ds_read_b128 v[118:121], v53 offset:256
	ds_read_b128 v[122:125], v53 offset:272
	ds_read_b128 v[126:129], v53 offset:288
	ds_read_b128 v[130:133], v53 offset:304
	ds_read_b128 v[134:137], v53 offset:320
	ds_read_b128 v[138:141], v53 offset:336
	ds_read_b128 v[142:145], v53 offset:352
	ds_read_b128 v[146:149], v53 offset:368
	ds_read_b128 v[150:153], v53 offset:384
	ds_read_b128 v[154:157], v53 offset:400
	ds_read_b128 v[158:161], v53 offset:416
	ds_read_b128 v[162:165], v53 offset:432
	ds_read_b128 v[166:169], v53 offset:448
	ds_read_b128 v[170:173], v53 offset:464
	ds_read_b128 v[174:177], v53 offset:480
	ds_read_b128 v[178:181], v53 offset:496
	s_addk_i32 s14, 0x200
	s_waitcnt vmcnt(12)
; #define LAS __attribute__((address_space(3)))
; __device__ __forceinline__ void p0_prologue(Frame& F, const Args& A, unsigned char* ws) {
;     ...
; #pragma unroll 4
;             for (int k = kbeg; k < kbeg + 128; ++k) {
;                 const float wv = w[(size_t)k * NMODC];
;                 const LAS f32x4* cr = (const LAS f32x4*)(cs + k * 32);
; #pragma unroll
;                 for (int b4 = 0; b4 < 8; ++b4) { const f32x4 cv = cr[b4]; acc[4 * b4] += cv[0] * wv; acc[4 * b4 + 1] += cv[1] * wv; acc[4 * b4 + 2] += cv[2] * wv; acc[4 * b4 + 3] += cv[3] * wv; }
;             }
	s_waitcnt lgkmcnt(0)
	v_pk_fma_f32 v[14:15], v[212:213], v[54:55], v[14:15] op_sel_hi:[0,1,1]
	v_pk_fma_f32 v[16:17], v[212:213], v[56:57], v[16:17] op_sel_hi:[0,1,1]
	v_pk_fma_f32 v[18:19], v[212:213], v[58:59], v[18:19] op_sel_hi:[0,1,1]
	v_pk_fma_f32 v[20:21], v[212:213], v[60:61], v[20:21] op_sel_hi:[0,1,1]
	v_pk_fma_f32 v[22:23], v[212:213], v[62:63], v[22:23] op_sel_hi:[0,1,1]
	v_pk_fma_f32 v[24:25], v[212:213], v[64:65], v[24:25] op_sel_hi:[0,1,1]
	v_pk_fma_f32 v[26:27], v[212:213], v[66:67], v[26:27] op_sel_hi:[0,1,1]
	v_pk_fma_f32 v[28:29], v[212:213], v[68:69], v[28:29] op_sel_hi:[0,1,1]
	v_pk_fma_f32 v[30:31], v[212:213], v[70:71], v[30:31] op_sel_hi:[0,1,1]
	v_pk_fma_f32 v[32:33], v[212:213], v[72:73], v[32:33] op_sel_hi:[0,1,1]
	v_pk_fma_f32 v[34:35], v[212:213], v[74:75], v[34:35] op_sel_hi:[0,1,1]
	v_pk_fma_f32 v[36:37], v[212:213], v[76:77], v[36:37] op_sel_hi:[0,1,1]
	v_pk_fma_f32 v[38:39], v[212:213], v[78:79], v[38:39] op_sel_hi:[0,1,1]
	v_pk_fma_f32 v[40:41], v[212:213], v[80:81], v[40:41] op_sel_hi:[0,1,1]
	v_pk_fma_f32 v[42:43], v[212:213], v[82:83], v[42:43] op_sel_hi:[0,1,1]
	v_pk_fma_f32 v[12:13], v[212:213], v[84:85], v[12:13] op_sel_hi:[0,1,1]
	v_pk_fma_f32 v[14:15], v[214:215], v[86:87], v[14:15] op_sel_hi:[0,1,1]
	v_pk_fma_f32 v[16:17], v[214:215], v[88:89], v[16:17] op_sel_hi:[0,1,1]
	v_pk_fma_f32 v[18:19], v[214:215], v[90:91], v[18:19] op_sel_hi:[0,1,1]
	v_pk_fma_f32 v[20:21], v[214:215], v[92:93], v[20:21] op_sel_hi:[0,1,1]
	v_pk_fma_f32 v[22:23], v[214:215], v[94:95], v[22:23] op_sel_hi:[0,1,1]
	v_pk_fma_f32 v[24:25], v[214:215], v[96:97], v[24:25] op_sel_hi:[0,1,1]
	v_pk_fma_f32 v[26:27], v[214:215], v[98:99], v[26:27] op_sel_hi:[0,1,1]
	v_pk_fma_f32 v[28:29], v[214:215], v[100:101], v[28:29] op_sel_hi:[0,1,1]
	v_pk_fma_f32 v[30:31], v[214:215], v[102:103], v[30:31] op_sel_hi:[0,1,1]
	v_pk_fma_f32 v[32:33], v[214:215], v[104:105], v[32:33] op_sel_hi:[0,1,1]
	v_pk_fma_f32 v[34:35], v[214:215], v[106:107], v[34:35] op_sel_hi:[0,1,1]
	v_pk_fma_f32 v[36:37], v[214:215], v[108:109], v[36:37] op_sel_hi:[0,1,1]
	v_pk_fma_f32 v[38:39], v[214:215], v[110:111], v[38:39] op_sel_hi:[0,1,1]
	v_pk_fma_f32 v[40:41], v[214:215], v[112:113], v[40:41] op_sel_hi:[0,1,1]
	v_pk_fma_f32 v[42:43], v[214:215], v[114:115], v[42:43] op_sel_hi:[0,1,1]
	v_pk_fma_f32 v[12:13], v[214:215], v[116:117], v[12:13] op_sel_hi:[0,1,1]
	v_pk_fma_f32 v[14:15], v[216:217], v[118:119], v[14:15] op_sel_hi:[0,1,1]
	v_pk_fma_f32 v[16:17], v[216:217], v[120:121], v[16:17] op_sel_hi:[0,1,1]
	v_pk_fma_f32 v[18:19], v[216:217], v[122:123], v[18:19] op_sel_hi:[0,1,1]
	v_pk_fma_f32 v[20:21], v[216:217], v[124:125], v[20:21] op_sel_hi:[0,1,1]
	v_pk_fma_f32 v[22:23], v[216:217], v[126:127], v[22:23] op_sel_hi:[0,1,1]
	v_pk_fma_f32 v[24:25], v[216:217], v[128:129], v[24:25] op_sel_hi:[0,1,1]
	v_pk_fma_f32 v[26:27], v[216:217], v[130:131], v[26:27] op_sel_hi:[0,1,1]
	v_pk_fma_f32 v[28:29], v[216:217], v[132:133], v[28:29] op_sel_hi:[0,1,1]
	v_pk_fma_f32 v[30:31], v[216:217], v[134:135], v[30:31] op_sel_hi:[0,1,1]
	v_pk_fma_f32 v[32:33], v[216:217], v[136:137], v[32:33] op_sel_hi:[0,1,1]
	v_pk_fma_f32 v[34:35], v[216:217], v[138:139], v[34:35] op_sel_hi:[0,1,1]
	v_pk_fma_f32 v[36:37], v[216:217], v[140:141], v[36:37] op_sel_hi:[0,1,1]
	v_pk_fma_f32 v[38:39], v[216:217], v[142:143], v[38:39] op_sel_hi:[0,1,1]
	v_pk_fma_f32 v[40:41], v[216:217], v[144:145], v[40:41] op_sel_hi:[0,1,1]
	v_pk_fma_f32 v[42:43], v[216:217], v[146:147], v[42:43] op_sel_hi:[0,1,1]
	v_pk_fma_f32 v[12:13], v[216:217], v[148:149], v[12:13] op_sel_hi:[0,1,1]
	v_pk_fma_f32 v[14:15], v[218:219], v[150:151], v[14:15] op_sel_hi:[0,1,1]
	v_pk_fma_f32 v[16:17], v[218:219], v[152:153], v[16:17] op_sel_hi:[0,1,1]
	v_pk_fma_f32 v[18:19], v[218:219], v[154:155], v[18:19] op_sel_hi:[0,1,1]
	v_pk_fma_f32 v[20:21], v[218:219], v[156:157], v[20:21] op_sel_hi:[0,1,1]
	v_pk_fma_f32 v[22:23], v[218:219], v[158:159], v[22:23] op_sel_hi:[0,1,1]
	v_pk_fma_f32 v[24:25], v[218:219], v[160:161], v[24:25] op_sel_hi:[0,1,1]
	v_pk_fma_f32 v[26:27], v[218:219], v[162:163], v[26:27] op_sel_hi:[0,1,1]
	v_pk_fma_f32 v[28:29], v[218:219], v[164:165], v[28:29] op_sel_hi:[0,1,1]
	v_pk_fma_f32 v[30:31], v[218:219], v[166:167], v[30:31] op_sel_hi:[0,1,1]
	v_pk_fma_f32 v[32:33], v[218:219], v[168:169], v[32:33] op_sel_hi:[0,1,1]
	v_pk_fma_f32 v[34:35], v[218:219], v[170:171], v[34:35] op_sel_hi:[0,1,1]
	v_pk_fma_f32 v[36:37], v[218:219], v[172:173], v[36:37] op_sel_hi:[0,1,1]
	v_pk_fma_f32 v[38:39], v[218:219], v[174:175], v[38:39] op_sel_hi:[0,1,1]
	v_pk_fma_f32 v[40:41], v[218:219], v[176:177], v[40:41] op_sel_hi:[0,1,1]
	v_pk_fma_f32 v[42:43], v[218:219], v[178:179], v[42:43] op_sel_hi:[0,1,1]
	v_pk_fma_f32 v[12:13], v[218:219], v[180:181], v[12:13] op_sel_hi:[0,1,1]
	s_add_u32 s16, s10, 0xd8000
	s_min_u32 s16, s16, 0x45c000
	v_lshl_add_u64 v[130:131], v[10:11], 0, s[16:17]
	global_load_dword v212, v[130:131], off
	s_add_u32 s16, s16, 0x9000
	v_lshl_add_u64 v[130:131], v[10:11], 0, s[16:17]
	global_load_dword v214, v[130:131], off
	s_add_u32 s16, s16, 0x9000
	v_lshl_add_u64 v[130:131], v[10:11], 0, s[16:17]
	global_load_dword v216, v[130:131], off
	s_add_u32 s16, s16, 0x9000
	v_lshl_add_u64 v[130:131], v[10:11], 0, s[16:17]
	global_load_dword v218, v[130:131], off
	v_mov_b32_e32 v53, s14
	ds_read_b128 v[54:57], v53
	ds_read_b128 v[58:61], v53 offset:16
	ds_read_b128 v[62:65], v53 offset:32
	ds_read_b128 v[66:69], v53 offset:48
	ds_read_b128 v[70:73], v53 offset:64
	ds_read_b128 v[74:77], v53 offset:80
	ds_read_b128 v[78:81], v53 offset:96
	ds_read_b128 v[82:85], v53 offset:112
	ds_read_b128 v[86:89], v53 offset:128
	ds_read_b128 v[90:93], v53 offset:144
	ds_read_b128 v[94:97], v53 offset:160
	ds_read_b128 v[98:101], v53 offset:176
	ds_read_b128 v[102:105], v53 offset:192
	ds_read_b128 v[106:109], v53 offset:208
	ds_read_b128 v[110:113], v53 offset:224
	ds_read_b128 v[114:117], v53 offset:240
	ds_read_b128 v[118:121], v53 offset:256
	ds_read_b128 v[122:125], v53 offset:272
	ds_read_b128 v[126:129], v53 offset:288
	ds_read_b128 v[130:133], v53 offset:304
	ds_read_b128 v[134:137], v53 offset:320
	ds_read_b128 v[138:141], v53 offset:336
	ds_read_b128 v[142:145], v53 offset:352
	ds_read_b128 v[146:149], v53 offset:368
	ds_read_b128 v[150:153], v53 offset:384
	ds_read_b128 v[154:157], v53 offset:400
	ds_read_b128 v[158:161], v53 offset:416
	ds_read_b128 v[162:165], v53 offset:432
	ds_read_b128 v[166:169], v53 offset:448
	ds_read_b128 v[170:173], v53 offset:464
	ds_read_b128 v[174:177], v53 offset:480
	ds_read_b128 v[178:181], v53 offset:496
	s_addk_i32 s14, 0x200
	s_waitcnt vmcnt(12)
; #define LAS __attribute__((address_space(3)))
; __device__ __forceinline__ void p0_prologue(Frame& F, const Args& A, unsigned char* ws) {
;     ...
; #pragma unroll 4
;             for (int k = kbeg; k < kbeg + 128; ++k) {
;                 const float wv = w[(size_t)k * NMODC];
;                 const LAS f32x4* cr = (const LAS f32x4*)(cs + k * 32);
; #pragma unroll
;                 for (int b4 = 0; b4 < 8; ++b4) { const f32x4 cv = cr[b4]; acc[4 * b4] += cv[0] * wv; acc[4 * b4 + 1] += cv[1] * wv; acc[4 * b4 + 2] += cv[2] * wv; acc[4 * b4 + 3] += cv[3] * wv; }
;             }
	s_waitcnt lgkmcnt(0)
	v_pk_fma_f32 v[14:15], v[220:221], v[54:55], v[14:15] op_sel_hi:[0,1,1]
	v_pk_fma_f32 v[16:17], v[220:221], v[56:57], v[16:17] op_sel_hi:[0,1,1]
	v_pk_fma_f32 v[18:19], v[220:221], v[58:59], v[18:19] op_sel_hi:[0,1,1]
	v_pk_fma_f32 v[20:21], v[220:221], v[60:61], v[20:21] op_sel_hi:[0,1,1]
	v_pk_fma_f32 v[22:23], v[220:221], v[62:63], v[22:23] op_sel_hi:[0,1,1]
	v_pk_fma_f32 v[24:25], v[220:221], v[64:65], v[24:25] op_sel_hi:[0,1,1]
	v_pk_fma_f32 v[26:27], v[220:221], v[66:67], v[26:27] op_sel_hi:[0,1,1]
	v_pk_fma_f32 v[28:29], v[220:221], v[68:69], v[28:29] op_sel_hi:[0,1,1]
	v_pk_fma_f32 v[30:31], v[220:221], v[70:71], v[30:31] op_sel_hi:[0,1,1]
	v_pk_fma_f32 v[32:33], v[220:221], v[72:73], v[32:33] op_sel_hi:[0,1,1]
	v_pk_fma_f32 v[34:35], v[220:221], v[74:75], v[34:35] op_sel_hi:[0,1,1]
	v_pk_fma_f32 v[36:37], v[220:221], v[76:77], v[36:37] op_sel_hi:[0,1,1]
	v_pk_fma_f32 v[38:39], v[220:221], v[78:79], v[38:39] op_sel_hi:[0,1,1]
	v_pk_fma_f32 v[40:41], v[220:221], v[80:81], v[40:41] op_sel_hi:[0,1,1]
	v_pk_fma_f32 v[42:43], v[220:221], v[82:83], v[42:43] op_sel_hi:[0,1,1]
	v_pk_fma_f32 v[12:13], v[220:221], v[84:85], v[12:13] op_sel_hi:[0,1,1]
	v_pk_fma_f32 v[14:15], v[222:223], v[86:87], v[14:15] op_sel_hi:[0,1,1]
	v_pk_fma_f32 v[16:17], v[222:223], v[88:89], v[16:17] op_sel_hi:[0,1,1]
	v_pk_fma_f32 v[18:19], v[222:223], v[90:91], v[18:19] op_sel_hi:[0,1,1]
	v_pk_fma_f32 v[20:21], v[222:223], v[92:93], v[20:21] op_sel_hi:[0,1,1]
	v_pk_fma_f32 v[22:23], v[222:223], v[94:95], v[22:23] op_sel_hi:[0,1,1]
	v_pk_fma_f32 v[24:25], v[222:223], v[96:97], v[24:25] op_sel_hi:[0,1,1]
	v_pk_fma_f32 v[26:27], v[222:223], v[98:99], v[26:27] op_sel_hi:[0,1,1]
	v_pk_fma_f32 v[28:29], v[222:223], v[100:101], v[28:29] op_sel_hi:[0,1,1]
	v_pk_fma_f32 v[30:31], v[222:223], v[102:103], v[30:31] op_sel_hi:[0,1,1]
	v_pk_fma_f32 v[32:33], v[222:223], v[104:105], v[32:33] op_sel_hi:[0,1,1]
	v_pk_fma_f32 v[34:35], v[222:223], v[106:107], v[34:35] op_sel_hi:[0,1,1]
	v_pk_fma_f32 v[36:37], v[222:223], v[108:109], v[36:37] op_sel_hi:[0,1,1]
	v_pk_fma_f32 v[38:39], v[222:223], v[110:111], v[38:39] op_sel_hi:[0,1,1]
	v_pk_fma_f32 v[40:41], v[222:223], v[112:113], v[40:41] op_sel_hi:[0,1,1]
	v_pk_fma_f32 v[42:43], v[222:223], v[114:115], v[42:43] op_sel_hi:[0,1,1]
	v_pk_fma_f32 v[12:13], v[222:223], v[116:117], v[12:13] op_sel_hi:[0,1,1]
	v_pk_fma_f32 v[14:15], v[234:235], v[118:119], v[14:15] op_sel_hi:[0,1,1]
	v_pk_fma_f32 v[16:17], v[234:235], v[120:121], v[16:17] op_sel_hi:[0,1,1]
	v_pk_fma_f32 v[18:19], v[234:235], v[122:123], v[18:19] op_sel_hi:[0,1,1]
	v_pk_fma_f32 v[20:21], v[234:235], v[124:125], v[20:21] op_sel_hi:[0,1,1]
	v_pk_fma_f32 v[22:23], v[234:235], v[126:127], v[22:23] op_sel_hi:[0,1,1]
	v_pk_fma_f32 v[24:25], v[234:235], v[128:129], v[24:25] op_sel_hi:[0,1,1]
	v_pk_fma_f32 v[26:27], v[234:235], v[130:131], v[26:27] op_sel_hi:[0,1,1]
	v_pk_fma_f32 v[28:29], v[234:235], v[132:133], v[28:29] op_sel_hi:[0,1,1]
	v_pk_fma_f32 v[30:31], v[234:235], v[134:135], v[30:31] op_sel_hi:[0,1,1]
	v_pk_fma_f32 v[32:33], v[234:235], v[136:137], v[32:33] op_sel_hi:[0,1,1]
	v_pk_fma_f32 v[34:35], v[234:235], v[138:139], v[34:35] op_sel_hi:[0,1,1]
	v_pk_fma_f32 v[36:37], v[234:235], v[140:141], v[36:37] op_sel_hi:[0,1,1]
	v_pk_fma_f32 v[38:39], v[234:235], v[142:143], v[38:39] op_sel_hi:[0,1,1]
	v_pk_fma_f32 v[40:41], v[234:235], v[144:145], v[40:41] op_sel_hi:[0,1,1]
	v_pk_fma_f32 v[42:43], v[234:235], v[146:147], v[42:43] op_sel_hi:[0,1,1]
	v_pk_fma_f32 v[12:13], v[234:235], v[148:149], v[12:13] op_sel_hi:[0,1,1]
	v_pk_fma_f32 v[14:15], v[236:237], v[150:151], v[14:15] op_sel_hi:[0,1,1]
	v_pk_fma_f32 v[16:17], v[236:237], v[152:153], v[16:17] op_sel_hi:[0,1,1]
	v_pk_fma_f32 v[18:19], v[236:237], v[154:155], v[18:19] op_sel_hi:[0,1,1]
	v_pk_fma_f32 v[20:21], v[236:237], v[156:157], v[20:21] op_sel_hi:[0,1,1]
	v_pk_fma_f32 v[22:23], v[236:237], v[158:159], v[22:23] op_sel_hi:[0,1,1]
	v_pk_fma_f32 v[24:25], v[236:237], v[160:161], v[24:25] op_sel_hi:[0,1,1]
	v_pk_fma_f32 v[26:27], v[236:237], v[162:163], v[26:27] op_sel_hi:[0,1,1]
	v_pk_fma_f32 v[28:29], v[236:237], v[164:165], v[28:29] op_sel_hi:[0,1,1]
	v_pk_fma_f32 v[30:31], v[236:237], v[166:167], v[30:31] op_sel_hi:[0,1,1]
	v_pk_fma_f32 v[32:33], v[236:237], v[168:169], v[32:33] op_sel_hi:[0,1,1]
	v_pk_fma_f32 v[34:35], v[236:237], v[170:171], v[34:35] op_sel_hi:[0,1,1]
	v_pk_fma_f32 v[36:37], v[236:237], v[172:173], v[36:37] op_sel_hi:[0,1,1]
	v_pk_fma_f32 v[38:39], v[236:237], v[174:175], v[38:39] op_sel_hi:[0,1,1]
	v_pk_fma_f32 v[40:41], v[236:237], v[176:177], v[40:41] op_sel_hi:[0,1,1]
	v_pk_fma_f32 v[42:43], v[236:237], v[178:179], v[42:43] op_sel_hi:[0,1,1]
	v_pk_fma_f32 v[12:13], v[236:237], v[180:181], v[12:13] op_sel_hi:[0,1,1]
	s_add_u32 s16, s10, 0xfc000
	s_min_u32 s16, s16, 0x45c000
	v_lshl_add_u64 v[130:131], v[10:11], 0, s[16:17]
	global_load_dword v220, v[130:131], off
	s_add_u32 s16, s16, 0x9000
	v_lshl_add_u64 v[130:131], v[10:11], 0, s[16:17]
	global_load_dword v222, v[130:131], off
	s_add_u32 s16, s16, 0x9000
	v_lshl_add_u64 v[130:131], v[10:11], 0, s[16:17]
	global_load_dword v234, v[130:131], off
	s_add_u32 s16, s16, 0x9000
	v_lshl_add_u64 v[130:131], v[10:11], 0, s[16:17]
	global_load_dword v236, v[130:131], off
	s_add_u32 s10, s10, 0x90000
	s_addc_u32 s11, s11, 0
	s_cmp_eq_u32 s10, 0x480000
	s_cbranch_scc0 .Ladaln_k_loop
; #define LAS __attribute__((address_space(3)))
; __device__ __forceinline__ void p0_prologue(Frame& F, const Args& A, unsigned char* ws) {
;     ...
;             __syncthreads();
;             LAS float* red = (LAS float*)F.lds;
; #pragma unroll
;             for (int b = 0; b < 32; ++b) red[(F.wave * 32 + b) * 64 + F.lane] = acc[b];
;             __syncthreads();
; #pragma unroll
;             for (int q = 0; q < 4; ++q) {
;                 const int idx = F.tid + NTHR * q, b = idx >> 6, cc = idx & 63;
;                 float sum = uni(A.in[3])[(size_t)l * NMODC + jb * 64 + cc];
; #pragma unroll
;                 for (int wv = 0; wv < 8; ++wv) sum += red[(wv * 32 + b) * 64 + cc];
;                 mod[((size_t)l * 32 + b) * NMODC + jb * 64 + cc] = sum;
;             }
;             __syncthreads();
	v_mov_b64_e32 v[10:11], s[0:1]
	s_barrier
	ds_write2st64_b32 v46, v14, v15 offset1:1
	ds_write2st64_b32 v46, v16, v17 offset0:2 offset1:3
	ds_write2st64_b32 v46, v18, v19 offset0:4 offset1:5
	ds_write2st64_b32 v46, v20, v21 offset0:6 offset1:7
	ds_write2st64_b32 v46, v22, v23 offset0:8 offset1:9
	ds_write2st64_b32 v46, v24, v25 offset0:10 offset1:11
	ds_write2st64_b32 v46, v26, v27 offset0:12 offset1:13
	ds_write2st64_b32 v46, v28, v29 offset0:14 offset1:15
	ds_write2st64_b32 v46, v30, v31 offset0:16 offset1:17
	ds_write2st64_b32 v46, v32, v33 offset0:18 offset1:19
	ds_write2st64_b32 v46, v34, v35 offset0:20 offset1:21
	ds_write2st64_b32 v46, v36, v37 offset0:22 offset1:23
	ds_write2st64_b32 v46, v38, v39 offset0:24 offset1:25
	ds_write2st64_b32 v46, v40, v41 offset0:26 offset1:27
	ds_write2st64_b32 v46, v42, v43 offset0:28 offset1:29
	ds_write2st64_b32 v46, v12, v13 offset0:30 offset1:31
	s_waitcnt lgkmcnt(0)
	s_barrier
	flat_load_dwordx2 v[10:11], v[10:11] offset:24
	s_mul_i32 s14, s12, 0x90
	s_mul_hi_i32 s15, s12, 0x9000
	s_mul_i32 s16, s12, 0x9000
	s_lshl_b64 s[10:11], s[12:13], 5
	s_sub_i32 s12, s33, s14
	s_lshl_b32 s12, s12, 6
	s_ashr_i32 s13, s12, 31
	s_lshl_b64 s[12:13], s[12:13], 2
	v_lshl_add_u64 v[20:21], s[10:11], 0, v[2:3]
	v_lshl_add_u64 v[22:23], v[0:1], 0, s[12:13]
	s_waitcnt vmcnt(0) lgkmcnt(0)
	v_readfirstlane_b32 s17, v10
	v_readfirstlane_b32 s14, v11
	s_add_u32 s16, s17, s16
	s_addc_u32 s15, s14, s15
	s_add_u32 s14, s16, s12
	s_addc_u32 s15, s15, s13
	v_lshl_add_u64 v[10:11], s[14:15], 0, v[192:193]
	flat_load_dword v26, v[10:11]
	ds_read2st64_b32 v[12:13], v47 offset1:32
	ds_read2st64_b32 v[14:15], v47 offset0:64 offset1:96
	ds_read2st64_b32 v[16:17], v47 offset0:128 offset1:160
	ds_read2st64_b32 v[18:19], v47 offset0:192 offset1:224
	v_mad_u64_u32 v[24:25], s[12:13], v20, s93, v[22:23]
	v_mad_i32_i24 v25, v21, s93, v25
	s_add_i32 s33, s33, s71
	s_cmpk_gt_i32 s33, 0x11f
	s_waitcnt vmcnt(0) lgkmcnt(0)
	v_add_f32_e32 v12, v26, v12
	v_add_f32_e32 v12, v12, v13
	v_add_f32_e32 v12, v12, v14
	v_add_f32_e32 v12, v12, v15
	v_add_f32_e32 v12, v12, v16
	v_add_f32_e32 v12, v12, v17
	v_add_f32_e32 v12, v12, v18
	v_add_f32_e32 v12, v12, v19
	flat_store_dword v[24:25], v12
	flat_load_dword v24, v[10:11]
	ds_read2st64_b32 v[16:17], v48 offset1:32
	v_lshl_add_u64 v[12:13], s[10:11], 0, v[4:5]
	v_mad_u64_u32 v[14:15], s[12:13], v12, s93, v[22:23]
	v_mad_i32_i24 v15, v13, s93, v15
	ds_read2st64_b32 v[12:13], v48 offset0:64 offset1:96
	ds_read2st64_b32 v[18:19], v48 offset0:128 offset1:160
	ds_read2st64_b32 v[20:21], v48 offset0:192 offset1:224
	s_waitcnt vmcnt(0) lgkmcnt(0)
	v_add_f32_e32 v16, v24, v16
	v_add_f32_e32 v16, v16, v17
	v_add_f32_e32 v12, v16, v12
	v_add_f32_e32 v12, v12, v13
	v_add_f32_e32 v12, v12, v18
	v_add_f32_e32 v12, v12, v19
	v_add_f32_e32 v12, v12, v20
	v_add_f32_e32 v12, v12, v21
	flat_store_dword v[14:15], v12
	flat_load_dword v24, v[10:11]
	ds_read2st64_b32 v[16:17], v49 offset1:32
	v_lshl_add_u64 v[12:13], s[10:11], 0, v[6:7]
	v_mad_u64_u32 v[14:15], s[12:13], v12, s93, v[22:23]
	v_mad_i32_i24 v15, v13, s93, v15
	ds_read2st64_b32 v[12:13], v49 offset0:64 offset1:96
	ds_read2st64_b32 v[18:19], v49 offset0:128 offset1:160
	ds_read2st64_b32 v[20:21], v49 offset0:192 offset1:224
	s_waitcnt vmcnt(0) lgkmcnt(0)
	v_add_f32_e32 v16, v24, v16
	v_add_f32_e32 v16, v16, v17
	v_add_f32_e32 v12, v16, v12
	v_add_f32_e32 v12, v12, v13
	v_add_f32_e32 v12, v12, v18
	v_add_f32_e32 v12, v12, v19
	v_add_f32_e32 v12, v12, v20
	v_add_f32_e32 v12, v12, v21
	flat_store_dword v[14:15], v12
	flat_load_dword v20, v[10:11]
	v_lshl_add_u64 v[10:11], s[10:11], 0, v[8:9]
	v_mad_u64_u32 v[12:13], s[10:11], v10, s93, v[22:23]
	v_mad_i32_i24 v13, v11, s93, v13
	ds_read2st64_b32 v[10:11], v50 offset1:32
	ds_read2st64_b32 v[14:15], v50 offset0:64 offset1:96
	ds_read2st64_b32 v[16:17], v50 offset0:128 offset1:160
	ds_read2st64_b32 v[18:19], v50 offset0:192 offset1:224
	s_waitcnt vmcnt(0) lgkmcnt(0)
	v_add_f32_e32 v10, v20, v10
	v_add_f32_e32 v10, v10, v11
	v_add_f32_e32 v10, v10, v14
	v_add_f32_e32 v10, v10, v15
	v_add_f32_e32 v10, v10, v16
	v_add_f32_e32 v10, v10, v17
	v_add_f32_e32 v10, v10, v18
	v_add_f32_e32 v10, v10, v19
	flat_store_dword v[12:13], v10
	s_waitcnt lgkmcnt(0)
	s_barrier
	s_cbranch_scc0 .LBB0_926
